# GEMM K-loops: per-segment s_setprio flips deleted, one static s_setprio 1 for waves 4-7 around each K-loop
# speedup vs baseline: 1.0107x; 1.0088x over previous
.LBB0_168:
	s_ashr_i32 s13, s12, 31
	s_lshl_b64 s[20:21], s[12:13], 20
	s_add_u32 s20, s0, s20
	s_addc_u32 s21, s1, s21
	s_and_b64 s[22:23], s[38:39], exec
	s_cselect_b32 s13, s21, s41
	s_cselect_b32 s47, s20, s40
	s_ashr_i32 s11, s10, 31
	s_lshl_b64 s[22:23], s[10:11], 20
	s_add_u32 s22, s2, s22
	s_addc_u32 s23, s4, s23
	s_and_b64 s[44:45], s[38:39], exec
	s_cselect_b32 s11, s23, s43
	s_cselect_b32 s48, s22, s42
	s_add_u32 s40, s40, 0x80080
	s_addc_u32 s41, s41, 0
	s_add_u32 s49, s42, 0x100
	v_mov_b32_e32 v2, 0
	s_addc_u32 s50, s43, 0
	s_mov_b32 s51, -2
	v_mov_b32_e32 v3, v2
	v_mov_b32_e32 v4, v2
	v_mov_b32_e32 v5, v2
	v_mov_b32_e32 v6, v2
	v_mov_b32_e32 v7, v2
	v_mov_b32_e32 v8, v2
	v_mov_b32_e32 v9, v2
	v_mov_b32_e32 v10, v2
	v_mov_b32_e32 v11, v2
	v_mov_b32_e32 v12, v2
	v_mov_b32_e32 v13, v2
	v_mov_b32_e32 v18, v2
	v_mov_b32_e32 v19, v2
	v_mov_b32_e32 v20, v2
	v_mov_b32_e32 v21, v2
	v_mov_b32_e32 v26, v2
	v_mov_b32_e32 v27, v2
	v_mov_b32_e32 v28, v2
	v_mov_b32_e32 v29, v2
	v_mov_b32_e32 v34, v2
	v_mov_b32_e32 v35, v2
	v_mov_b32_e32 v36, v2
	v_mov_b32_e32 v37, v2
	v_mov_b32_e32 v42, v2
	v_mov_b32_e32 v43, v2
	v_mov_b32_e32 v44, v2
	v_mov_b32_e32 v45, v2
	v_mov_b32_e32 v50, v2
	v_mov_b32_e32 v51, v2
	v_mov_b32_e32 v52, v2
	v_mov_b32_e32 v53, v2
	v_mov_b32_e32 v14, v2
	v_mov_b32_e32 v15, v2
	v_mov_b32_e32 v16, v2
	v_mov_b32_e32 v17, v2
	v_mov_b32_e32 v22, v2
	v_mov_b32_e32 v23, v2
	v_mov_b32_e32 v24, v2
	v_mov_b32_e32 v25, v2
	v_mov_b32_e32 v30, v2
	v_mov_b32_e32 v31, v2
	v_mov_b32_e32 v32, v2
	v_mov_b32_e32 v33, v2
	v_mov_b32_e32 v38, v2
	v_mov_b32_e32 v39, v2
	v_mov_b32_e32 v40, v2
	v_mov_b32_e32 v41, v2
	v_mov_b32_e32 v46, v2
	v_mov_b32_e32 v47, v2
	v_mov_b32_e32 v48, v2
	v_mov_b32_e32 v49, v2
	v_mov_b32_e32 v54, v2
	v_mov_b32_e32 v55, v2
	v_mov_b32_e32 v56, v2
	v_mov_b32_e32 v57, v2
	v_mov_b32_e32 v58, v2
	v_mov_b32_e32 v59, v2
	v_mov_b32_e32 v60, v2
	v_mov_b32_e32 v61, v2
	v_mov_b32_e32 v62, v2
	v_mov_b32_e32 v63, v2
	v_mov_b32_e32 v64, v2
	v_mov_b32_e32 v65, v2
	v_mov_b32_e32 v66, v2
	v_mov_b32_e32 v67, v2
	v_mov_b32_e32 v68, v2
	v_mov_b32_e32 v69, v2
	v_mov_b32_e32 v70, v2
	v_mov_b32_e32 v71, v2
	v_mov_b32_e32 v72, v2
	v_mov_b32_e32 v73, v2
	v_mov_b32_e32 v74, v2
	v_mov_b32_e32 v75, v2
	v_mov_b32_e32 v76, v2
	v_mov_b32_e32 v77, v2
	v_mov_b32_e32 v82, v2
	v_mov_b32_e32 v83, v2
	v_mov_b32_e32 v84, v2
	v_mov_b32_e32 v85, v2
	v_mov_b32_e32 v90, v2
	v_mov_b32_e32 v91, v2
	v_mov_b32_e32 v92, v2
	v_mov_b32_e32 v93, v2
	v_mov_b32_e32 v98, v2
	v_mov_b32_e32 v99, v2
	v_mov_b32_e32 v100, v2
	v_mov_b32_e32 v101, v2
	v_mov_b32_e32 v106, v2
	v_mov_b32_e32 v107, v2
	v_mov_b32_e32 v108, v2
	v_mov_b32_e32 v109, v2
	v_mov_b32_e32 v114, v2
	v_mov_b32_e32 v115, v2
	v_mov_b32_e32 v116, v2
	v_mov_b32_e32 v117, v2
	v_mov_b32_e32 v78, v2
	v_mov_b32_e32 v79, v2
	v_mov_b32_e32 v80, v2
	v_mov_b32_e32 v81, v2
	v_mov_b32_e32 v86, v2
	v_mov_b32_e32 v87, v2
	v_mov_b32_e32 v88, v2
	v_mov_b32_e32 v89, v2
	v_mov_b32_e32 v94, v2
	v_mov_b32_e32 v95, v2
	v_mov_b32_e32 v96, v2
	v_mov_b32_e32 v97, v2
	v_mov_b32_e32 v102, v2
	v_mov_b32_e32 v103, v2
	v_mov_b32_e32 v104, v2
	v_mov_b32_e32 v105, v2
	v_mov_b32_e32 v110, v2
	v_mov_b32_e32 v111, v2
	v_mov_b32_e32 v112, v2
	v_mov_b32_e32 v113, v2
	v_mov_b32_e32 v118, v2
	v_mov_b32_e32 v119, v2
	v_mov_b32_e32 v120, v2
	v_mov_b32_e32 v121, v2
	v_mov_b32_e32 v122, v2
	v_mov_b32_e32 v123, v2
	v_mov_b32_e32 v124, v2
	v_mov_b32_e32 v125, v2
	v_mov_b32_e32 v126, v2
	v_mov_b32_e32 v127, v2
	v_mov_b32_e32 v128, v2
	v_mov_b32_e32 v129, v2
	v_readfirstlane_b32 s98, v146
	s_nop 3
	s_lshr_b32 s98, s98, 6
	s_cmp_ge_u32 s98, 4
	s_cbranch_scc0 .Lgprio0
	s_setprio 1
.Lgprio0:
.LBB0_169:
	s_add_u32 s42, s40, 0xfff80080
	s_addc_u32 s43, s41, -1
	s_add_i32 s52, 0, 0x10000
	s_cmp_eq_u32 s51, 28
	s_cselect_b32 s45, s13, s43
	s_cselect_b32 s44, s47, s42
	s_cselect_b32 s43, s11, s50
	s_cselect_b32 s42, s48, s49
	s_add_i32 s54, 0, 0x14000
	v_add_u32_e32 v142, s52, v175
	v_add_u32_e32 v154, s54, v175
	ds_read_b128 v[130:133], v142
	ds_read_b128 v[134:137], v142 offset:1024
	ds_read_b128 v[138:141], v142 offset:2048
	ds_read_b128 v[142:145], v142 offset:3072
	ds_read_b128 v[170:173], v154
	ds_read_b128 v[184:187], v154 offset:1024
	ds_read_b128 v[188:191], v154 offset:2048
	ds_read_b128 v[192:195], v154 offset:3072
	s_add_i32 m0, s14, 0xc000
	ds_read_b128 v[196:199], v183
	ds_read_b128 v[200:203], v183 offset:1024
	ds_read_b128 v[210:213], v183 offset:2048
	ds_read_b128 v[214:217], v183 offset:3072
	ds_read_b128 v[218:221], v183 offset:4096
	ds_read_b128 v[222:225], v183 offset:5120
	ds_read_b128 v[226:229], v183 offset:6144
	ds_read_b128 v[230:233], v183 offset:7168
	global_load_lds_dwordx4 v166, s[40:41]
	s_add_i32 m0, s14, 0xe000
	s_nop 0
	global_load_lds_dwordx4 v168, s[40:41]
	s_waitcnt vmcnt(8)
	s_waitcnt lgkmcnt(0)
	s_barrier
	s_waitcnt lgkmcnt(0)
	v_mfma_f32_16x16x32_bf16 v[126:129], v[130:133], v[196:199], v[126:129]
	v_mfma_f32_16x16x32_bf16 v[122:125], v[138:141], v[196:199], v[122:125]
	v_mfma_f32_16x16x32_bf16 v[118:121], v[130:133], v[210:213], v[118:121]
	v_mfma_f32_16x16x32_bf16 v[110:113], v[138:141], v[210:213], v[110:113]
	v_mfma_f32_16x16x32_bf16 v[102:105], v[130:133], v[218:221], v[102:105]
	v_mfma_f32_16x16x32_bf16 v[94:97], v[138:141], v[218:221], v[94:97]
	v_mfma_f32_16x16x32_bf16 v[86:89], v[130:133], v[226:229], v[86:89]
	v_mfma_f32_16x16x32_bf16 v[78:81], v[138:141], v[226:229], v[78:81]
	v_mfma_f32_16x16x32_bf16 v[126:129], v[134:137], v[200:203], v[126:129]
	v_mfma_f32_16x16x32_bf16 v[122:125], v[142:145], v[200:203], v[122:125]
	v_mfma_f32_16x16x32_bf16 v[118:121], v[134:137], v[214:217], v[118:121]
	v_mfma_f32_16x16x32_bf16 v[110:113], v[142:145], v[214:217], v[110:113]
	v_mfma_f32_16x16x32_bf16 v[102:105], v[134:137], v[222:225], v[102:105]
	v_mfma_f32_16x16x32_bf16 v[94:97], v[142:145], v[222:225], v[94:97]
	v_mfma_f32_16x16x32_bf16 v[86:89], v[134:137], v[230:233], v[86:89]
	v_mfma_f32_16x16x32_bf16 v[78:81], v[142:145], v[230:233], v[78:81]
	v_mfma_f32_16x16x32_bf16 v[114:117], v[170:173], v[196:199], v[114:117]
	v_mfma_f32_16x16x32_bf16 v[106:109], v[188:191], v[196:199], v[106:109]
	v_mfma_f32_16x16x32_bf16 v[98:101], v[170:173], v[210:213], v[98:101]
	v_mfma_f32_16x16x32_bf16 v[90:93], v[188:191], v[210:213], v[90:93]
	v_mfma_f32_16x16x32_bf16 v[82:85], v[170:173], v[218:221], v[82:85]
	v_mfma_f32_16x16x32_bf16 v[74:77], v[188:191], v[218:221], v[74:77]
	v_mfma_f32_16x16x32_bf16 v[70:73], v[170:173], v[226:229], v[70:73]
	v_mfma_f32_16x16x32_bf16 v[66:69], v[188:191], v[226:229], v[66:69]
	v_mfma_f32_16x16x32_bf16 v[114:117], v[184:187], v[200:203], v[114:117]
	v_mfma_f32_16x16x32_bf16 v[106:109], v[192:195], v[200:203], v[106:109]
	v_mfma_f32_16x16x32_bf16 v[98:101], v[184:187], v[214:217], v[98:101]
	v_mfma_f32_16x16x32_bf16 v[90:93], v[192:195], v[214:217], v[90:93]
	v_mfma_f32_16x16x32_bf16 v[82:85], v[184:187], v[222:225], v[82:85]
	v_mfma_f32_16x16x32_bf16 v[74:77], v[192:195], v[222:225], v[74:77]
	v_mfma_f32_16x16x32_bf16 v[70:73], v[184:187], v[230:233], v[70:73]
	v_mfma_f32_16x16x32_bf16 v[66:69], v[192:195], v[230:233], v[66:69]
	s_barrier
	s_add_i32 s52, s52, s5
	v_lshl_add_u64 v[154:155], s[42:43], 0, v[162:163]
	s_mov_b32 m0, s52
	ds_read_b128 v[196:199], v183 offset:16384
	ds_read_b128 v[200:203], v183 offset:17408
	ds_read_b128 v[210:213], v183 offset:18432
	ds_read_b128 v[214:217], v183 offset:19456
	ds_read_b128 v[218:221], v183 offset:20480
	ds_read_b128 v[222:225], v183 offset:21504
	ds_read_b128 v[226:229], v183 offset:22528
	ds_read_b128 v[230:233], v183 offset:23552
	global_load_lds_dwordx4 v[154:155], off
	s_add_i32 m0, s52, 0x2000
	s_add_u32 s52, s42, 0x80000
	v_lshl_add_u64 v[156:157], s[42:43], 0, v[158:159]
	s_addc_u32 s53, s43, 0
	s_add_i32 s54, s54, s5
	global_load_lds_dwordx4 v[156:157], off
	s_mov_b32 m0, s54
	v_lshl_add_u64 v[180:181], s[44:45], 0, v[160:161]
	global_load_lds_dwordx4 v162, s[52:53]
	s_add_i32 m0, s54, 0x2000
	s_nop 0
	global_load_lds_dwordx4 v158, s[52:53]
	v_lshl_add_u64 v[176:177], s[44:45], 0, v[164:165]
	s_mov_b32 m0, s14
	s_nop 0
	global_load_lds_dwordx4 v[176:177], off
	s_mov_b32 m0, s15
	s_nop 0
	global_load_lds_dwordx4 v[180:181], off
	s_waitcnt vmcnt(8)
	s_waitcnt lgkmcnt(0)
	s_barrier
	s_waitcnt lgkmcnt(0)
	v_mfma_f32_16x16x32_bf16 v[62:65], v[130:133], v[196:199], v[62:65]
	v_mfma_f32_16x16x32_bf16 v[58:61], v[138:141], v[196:199], v[58:61]
	v_mfma_f32_16x16x32_bf16 v[54:57], v[130:133], v[210:213], v[54:57]
	v_mfma_f32_16x16x32_bf16 v[46:49], v[138:141], v[210:213], v[46:49]
	v_mfma_f32_16x16x32_bf16 v[38:41], v[130:133], v[218:221], v[38:41]
	v_mfma_f32_16x16x32_bf16 v[30:33], v[138:141], v[218:221], v[30:33]
	v_mfma_f32_16x16x32_bf16 v[22:25], v[130:133], v[226:229], v[22:25]
	v_mfma_f32_16x16x32_bf16 v[14:17], v[138:141], v[226:229], v[14:17]
	v_mfma_f32_16x16x32_bf16 v[62:65], v[134:137], v[200:203], v[62:65]
	v_mfma_f32_16x16x32_bf16 v[58:61], v[142:145], v[200:203], v[58:61]
	v_mfma_f32_16x16x32_bf16 v[54:57], v[134:137], v[214:217], v[54:57]
	v_mfma_f32_16x16x32_bf16 v[46:49], v[142:145], v[214:217], v[46:49]
	v_mfma_f32_16x16x32_bf16 v[38:41], v[134:137], v[222:225], v[38:41]
	v_mfma_f32_16x16x32_bf16 v[30:33], v[142:145], v[222:225], v[30:33]
	v_mfma_f32_16x16x32_bf16 v[22:25], v[134:137], v[230:233], v[22:25]
	v_mfma_f32_16x16x32_bf16 v[14:17], v[142:145], v[230:233], v[14:17]
	v_mfma_f32_16x16x32_bf16 v[50:53], v[170:173], v[196:199], v[50:53]
	v_mfma_f32_16x16x32_bf16 v[42:45], v[188:191], v[196:199], v[42:45]
	v_mfma_f32_16x16x32_bf16 v[34:37], v[170:173], v[210:213], v[34:37]
	v_mfma_f32_16x16x32_bf16 v[26:29], v[188:191], v[210:213], v[26:29]
	v_mfma_f32_16x16x32_bf16 v[18:21], v[170:173], v[218:221], v[18:21]
	v_mfma_f32_16x16x32_bf16 v[10:13], v[188:191], v[218:221], v[10:13]
	v_mfma_f32_16x16x32_bf16 v[6:9], v[170:173], v[226:229], v[6:9]
	v_mfma_f32_16x16x32_bf16 v[2:5], v[188:191], v[226:229], v[2:5]
	v_mfma_f32_16x16x32_bf16 v[50:53], v[184:187], v[200:203], v[50:53]
	v_mfma_f32_16x16x32_bf16 v[42:45], v[192:195], v[200:203], v[42:45]
	v_mfma_f32_16x16x32_bf16 v[34:37], v[184:187], v[214:217], v[34:37]
	v_mfma_f32_16x16x32_bf16 v[26:29], v[192:195], v[214:217], v[26:29]
	v_mfma_f32_16x16x32_bf16 v[18:21], v[184:187], v[222:225], v[18:21]
	v_mfma_f32_16x16x32_bf16 v[10:13], v[192:195], v[222:225], v[10:13]
	v_mfma_f32_16x16x32_bf16 v[6:9], v[184:187], v[230:233], v[6:9]
	v_mfma_f32_16x16x32_bf16 v[2:5], v[192:195], v[230:233], v[2:5]
	s_barrier
	s_add_i32 s52, 0, 0x18000
	s_add_i32 s53, 0, 0x1c000
	v_add_u32_e32 v142, s52, v175
	v_add_u32_e32 v174, s53, v175
	ds_read_b128 v[130:133], v142
	ds_read_b128 v[134:137], v142 offset:1024
	ds_read_b128 v[138:141], v142 offset:2048
	ds_read_b128 v[142:145], v142 offset:3072
	ds_read_b128 v[170:173], v174
	ds_read_b128 v[184:187], v174 offset:1024
	ds_read_b128 v[188:191], v174 offset:2048
	ds_read_b128 v[192:195], v174 offset:3072
	s_add_u32 s44, s44, 0x80000
	s_addc_u32 s45, s45, 0
	s_mov_b32 m0, s16
	ds_read_b128 v[196:199], v183 offset:32768
	ds_read_b128 v[200:203], v183 offset:33792
	ds_read_b128 v[210:213], v183 offset:34816
	ds_read_b128 v[214:217], v183 offset:35840
	ds_read_b128 v[218:221], v183 offset:36864
	ds_read_b128 v[222:225], v183 offset:37888
	ds_read_b128 v[226:229], v183 offset:38912
	ds_read_b128 v[230:233], v183 offset:39936
	global_load_lds_dwordx4 v164, s[44:45]
	s_mov_b32 m0, s18
	s_nop 0
	global_load_lds_dwordx4 v160, s[44:45]
	s_waitcnt vmcnt(8)
	s_waitcnt lgkmcnt(0)
	s_barrier
	s_waitcnt lgkmcnt(0)
	v_mfma_f32_16x16x32_bf16 v[126:129], v[130:133], v[196:199], v[126:129]
	v_mfma_f32_16x16x32_bf16 v[122:125], v[138:141], v[196:199], v[122:125]
	v_mfma_f32_16x16x32_bf16 v[118:121], v[130:133], v[210:213], v[118:121]
	v_mfma_f32_16x16x32_bf16 v[110:113], v[138:141], v[210:213], v[110:113]
	v_mfma_f32_16x16x32_bf16 v[102:105], v[130:133], v[218:221], v[102:105]
	v_mfma_f32_16x16x32_bf16 v[94:97], v[138:141], v[218:221], v[94:97]
	v_mfma_f32_16x16x32_bf16 v[86:89], v[130:133], v[226:229], v[86:89]
	v_mfma_f32_16x16x32_bf16 v[78:81], v[138:141], v[226:229], v[78:81]
	v_mfma_f32_16x16x32_bf16 v[126:129], v[134:137], v[200:203], v[126:129]
	v_mfma_f32_16x16x32_bf16 v[122:125], v[142:145], v[200:203], v[122:125]
	v_mfma_f32_16x16x32_bf16 v[118:121], v[134:137], v[214:217], v[118:121]
	v_mfma_f32_16x16x32_bf16 v[110:113], v[142:145], v[214:217], v[110:113]
	v_mfma_f32_16x16x32_bf16 v[102:105], v[134:137], v[222:225], v[102:105]
	v_mfma_f32_16x16x32_bf16 v[94:97], v[142:145], v[222:225], v[94:97]
	v_mfma_f32_16x16x32_bf16 v[86:89], v[134:137], v[230:233], v[86:89]
	v_mfma_f32_16x16x32_bf16 v[78:81], v[142:145], v[230:233], v[78:81]
	v_mfma_f32_16x16x32_bf16 v[114:117], v[170:173], v[196:199], v[114:117]
	v_mfma_f32_16x16x32_bf16 v[106:109], v[188:191], v[196:199], v[106:109]
	v_mfma_f32_16x16x32_bf16 v[98:101], v[170:173], v[210:213], v[98:101]
	v_mfma_f32_16x16x32_bf16 v[90:93], v[188:191], v[210:213], v[90:93]
	v_mfma_f32_16x16x32_bf16 v[82:85], v[170:173], v[218:221], v[82:85]
	v_mfma_f32_16x16x32_bf16 v[74:77], v[188:191], v[218:221], v[74:77]
	v_mfma_f32_16x16x32_bf16 v[70:73], v[170:173], v[226:229], v[70:73]
	v_mfma_f32_16x16x32_bf16 v[66:69], v[188:191], v[226:229], v[66:69]
	v_mfma_f32_16x16x32_bf16 v[114:117], v[184:187], v[200:203], v[114:117]
	v_mfma_f32_16x16x32_bf16 v[106:109], v[192:195], v[200:203], v[106:109]
	v_mfma_f32_16x16x32_bf16 v[98:101], v[184:187], v[214:217], v[98:101]
	v_mfma_f32_16x16x32_bf16 v[90:93], v[192:195], v[214:217], v[90:93]
	v_mfma_f32_16x16x32_bf16 v[82:85], v[184:187], v[222:225], v[82:85]
	v_mfma_f32_16x16x32_bf16 v[74:77], v[192:195], v[222:225], v[74:77]
	v_mfma_f32_16x16x32_bf16 v[70:73], v[184:187], v[230:233], v[70:73]
	v_mfma_f32_16x16x32_bf16 v[66:69], v[192:195], v[230:233], v[66:69]
	s_barrier
	s_add_i32 s44, s52, s5
	v_lshl_add_u64 v[154:155], v[154:155], 0, s[34:35]
	s_mov_b32 m0, s44
	ds_read_b128 v[196:199], v183 offset:49152
	ds_read_b128 v[200:203], v183 offset:50176
	ds_read_b128 v[210:213], v183 offset:51200
	ds_read_b128 v[214:217], v183 offset:52224
	ds_read_b128 v[218:221], v183 offset:53248
	ds_read_b128 v[222:225], v183 offset:54272
	ds_read_b128 v[226:229], v183 offset:55296
	ds_read_b128 v[230:233], v183 offset:56320
	global_load_lds_dwordx4 v[154:155], off
	s_add_i32 m0, s44, 0x2000
	s_add_u32 s42, s42, 0x80080
	v_lshl_add_u64 v[154:155], v[156:157], 0, s[34:35]
	s_addc_u32 s43, s43, 0
	s_add_i32 s44, s53, s5
	global_load_lds_dwordx4 v[154:155], off
	s_mov_b32 m0, s44
	s_nop 0
	global_load_lds_dwordx4 v162, s[42:43]
	s_add_i32 m0, s44, 0x2000
	s_nop 0
	global_load_lds_dwordx4 v158, s[42:43]
	v_lshl_add_u64 v[154:155], v[176:177], 0, s[34:35]
	s_mov_b32 m0, s19
	s_nop 0
	global_load_lds_dwordx4 v[154:155], off
	v_lshl_add_u64 v[154:155], v[180:181], 0, s[34:35]
	s_mov_b32 m0, s25
	s_nop 0
	global_load_lds_dwordx4 v[154:155], off
	s_waitcnt vmcnt(8)
	s_waitcnt lgkmcnt(0)
	s_barrier
	s_waitcnt lgkmcnt(0)
	v_mfma_f32_16x16x32_bf16 v[62:65], v[130:133], v[196:199], v[62:65]
	v_mfma_f32_16x16x32_bf16 v[58:61], v[138:141], v[196:199], v[58:61]
	v_mfma_f32_16x16x32_bf16 v[54:57], v[130:133], v[210:213], v[54:57]
	v_mfma_f32_16x16x32_bf16 v[46:49], v[138:141], v[210:213], v[46:49]
	v_mfma_f32_16x16x32_bf16 v[38:41], v[130:133], v[218:221], v[38:41]
	v_mfma_f32_16x16x32_bf16 v[30:33], v[138:141], v[218:221], v[30:33]
	v_mfma_f32_16x16x32_bf16 v[22:25], v[130:133], v[226:229], v[22:25]
	v_mfma_f32_16x16x32_bf16 v[14:17], v[138:141], v[226:229], v[14:17]
	v_mfma_f32_16x16x32_bf16 v[62:65], v[134:137], v[200:203], v[62:65]
	v_mfma_f32_16x16x32_bf16 v[58:61], v[142:145], v[200:203], v[58:61]
	v_mfma_f32_16x16x32_bf16 v[54:57], v[134:137], v[214:217], v[54:57]
	v_mfma_f32_16x16x32_bf16 v[46:49], v[142:145], v[214:217], v[46:49]
	v_mfma_f32_16x16x32_bf16 v[38:41], v[134:137], v[222:225], v[38:41]
	v_mfma_f32_16x16x32_bf16 v[30:33], v[142:145], v[222:225], v[30:33]
	v_mfma_f32_16x16x32_bf16 v[22:25], v[134:137], v[230:233], v[22:25]
	v_mfma_f32_16x16x32_bf16 v[14:17], v[142:145], v[230:233], v[14:17]
	v_mfma_f32_16x16x32_bf16 v[50:53], v[170:173], v[196:199], v[50:53]
	v_mfma_f32_16x16x32_bf16 v[42:45], v[188:191], v[196:199], v[42:45]
	v_mfma_f32_16x16x32_bf16 v[34:37], v[170:173], v[210:213], v[34:37]
	v_mfma_f32_16x16x32_bf16 v[26:29], v[188:191], v[210:213], v[26:29]
	v_mfma_f32_16x16x32_bf16 v[18:21], v[170:173], v[218:221], v[18:21]
	v_mfma_f32_16x16x32_bf16 v[10:13], v[188:191], v[218:221], v[10:13]
	v_mfma_f32_16x16x32_bf16 v[6:9], v[170:173], v[226:229], v[6:9]
	v_mfma_f32_16x16x32_bf16 v[2:5], v[188:191], v[226:229], v[2:5]
	v_mfma_f32_16x16x32_bf16 v[50:53], v[184:187], v[200:203], v[50:53]
	v_mfma_f32_16x16x32_bf16 v[42:45], v[192:195], v[200:203], v[42:45]
	v_mfma_f32_16x16x32_bf16 v[34:37], v[184:187], v[214:217], v[34:37]
	v_mfma_f32_16x16x32_bf16 v[26:29], v[192:195], v[214:217], v[26:29]
	v_mfma_f32_16x16x32_bf16 v[18:21], v[184:187], v[222:225], v[18:21]
	v_mfma_f32_16x16x32_bf16 v[10:13], v[192:195], v[222:225], v[10:13]
	v_mfma_f32_16x16x32_bf16 v[6:9], v[184:187], v[230:233], v[6:9]
	v_mfma_f32_16x16x32_bf16 v[2:5], v[192:195], v[230:233], v[2:5]
	s_barrier
	s_add_i32 s51, s51, 2
	s_add_u32 s40, s40, 0x100
	s_addc_u32 s41, s41, 0
	s_add_u32 s49, s49, 0x100
	s_addc_u32 s50, s50, 0
	s_cmp_gt_u32 s51, 29
	s_cbranch_scc0 .LBB0_169
	s_setprio 0
	s_and_b64 vcc, exec, s[8:9]
	s_cbranch_vccz .LBB0_172
	s_barrier

.LBB0_515:
	s_ashr_i32 s21, s20, 31
	s_lshl_b64 s[22:23], s[20:21], 20
	s_add_u32 s22, s0, s22
	s_addc_u32 s23, s1, s23
	s_and_b64 s[42:43], s[40:41], exec
	s_cselect_b32 s21, s23, s45
	s_cselect_b32 s50, s22, s44
	s_ashr_i32 s13, s12, 31
	s_lshl_b64 s[42:43], s[12:13], 20
	s_add_u32 s42, s2, s42
	s_addc_u32 s43, s4, s43
	s_and_b64 s[48:49], s[40:41], exec
	s_cselect_b32 s13, s43, s47
	s_cselect_b32 s51, s42, s46
	s_add_u32 s44, s44, 0x80080
	s_addc_u32 s45, s45, 0
	s_add_u32 s55, s46, 0x100
	v_mov_b32_e32 v2, 0
	s_addc_u32 s56, s47, 0
	s_mov_b32 s57, -2
	s_waitcnt lgkmcnt(0)
	v_mov_b32_e32 v3, v2
	v_mov_b32_e32 v4, v2
	v_mov_b32_e32 v5, v2
	v_mov_b32_e32 v6, v2
	v_mov_b32_e32 v7, v2
	v_mov_b32_e32 v8, v2
	v_mov_b32_e32 v9, v2
	v_mov_b32_e32 v18, v2
	v_mov_b32_e32 v19, v2
	v_mov_b32_e32 v20, v2
	v_mov_b32_e32 v21, v2
	v_mov_b32_e32 v22, v2
	v_mov_b32_e32 v23, v2
	v_mov_b32_e32 v24, v2
	v_mov_b32_e32 v25, v2
	v_mov_b32_e32 v34, v2
	v_mov_b32_e32 v35, v2
	v_mov_b32_e32 v36, v2
	v_mov_b32_e32 v37, v2
	v_mov_b32_e32 v38, v2
	v_mov_b32_e32 v39, v2
	v_mov_b32_e32 v40, v2
	v_mov_b32_e32 v41, v2
	v_mov_b32_e32 v50, v2
	v_mov_b32_e32 v51, v2
	v_mov_b32_e32 v52, v2
	v_mov_b32_e32 v53, v2
	v_mov_b32_e32 v54, v2
	v_mov_b32_e32 v55, v2
	v_mov_b32_e32 v56, v2
	v_mov_b32_e32 v57, v2
	v_mov_b32_e32 v10, v2
	v_mov_b32_e32 v11, v2
	v_mov_b32_e32 v12, v2
	v_mov_b32_e32 v13, v2
	v_mov_b32_e32 v14, v2
	v_mov_b32_e32 v15, v2
	v_mov_b32_e32 v16, v2
	v_mov_b32_e32 v17, v2
	v_mov_b32_e32 v26, v2
	v_mov_b32_e32 v27, v2
	v_mov_b32_e32 v28, v2
	v_mov_b32_e32 v29, v2
	v_mov_b32_e32 v30, v2
	v_mov_b32_e32 v31, v2
	v_mov_b32_e32 v32, v2
	v_mov_b32_e32 v33, v2
	v_mov_b32_e32 v42, v2
	v_mov_b32_e32 v43, v2
	v_mov_b32_e32 v44, v2
	v_mov_b32_e32 v45, v2
	v_mov_b32_e32 v46, v2
	v_mov_b32_e32 v47, v2
	v_mov_b32_e32 v48, v2
	v_mov_b32_e32 v49, v2
	v_mov_b32_e32 v58, v2
	v_mov_b32_e32 v59, v2
	v_mov_b32_e32 v60, v2
	v_mov_b32_e32 v61, v2
	v_mov_b32_e32 v62, v2
	v_mov_b32_e32 v63, v2
	v_mov_b32_e32 v64, v2
	v_mov_b32_e32 v65, v2
	v_mov_b32_e32 v66, v2
	v_mov_b32_e32 v67, v2
	v_mov_b32_e32 v68, v2
	v_mov_b32_e32 v69, v2
	v_mov_b32_e32 v70, v2
	v_mov_b32_e32 v71, v2
	v_mov_b32_e32 v72, v2
	v_mov_b32_e32 v73, v2
	v_mov_b32_e32 v90, v2
	v_mov_b32_e32 v91, v2
	v_mov_b32_e32 v92, v2
	v_mov_b32_e32 v93, v2
	v_mov_b32_e32 v94, v2
	v_mov_b32_e32 v95, v2
	v_mov_b32_e32 v96, v2
	v_mov_b32_e32 v97, v2
	v_mov_b32_e32 v114, v2
	v_mov_b32_e32 v115, v2
	v_mov_b32_e32 v116, v2
	v_mov_b32_e32 v117, v2
	v_mov_b32_e32 v118, v2
	v_mov_b32_e32 v119, v2
	v_mov_b32_e32 v120, v2
	v_mov_b32_e32 v121, v2
	v_mov_b32_e32 v130, v2
	v_mov_b32_e32 v131, v2
	v_mov_b32_e32 v132, v2
	v_mov_b32_e32 v133, v2
	v_mov_b32_e32 v134, v2
	v_mov_b32_e32 v135, v2
	v_mov_b32_e32 v136, v2
	v_mov_b32_e32 v137, v2
	v_mov_b32_e32 v74, v2
	v_mov_b32_e32 v75, v2
	v_mov_b32_e32 v76, v2
	v_mov_b32_e32 v77, v2
	v_mov_b32_e32 v78, v2
	v_mov_b32_e32 v79, v2
	v_mov_b32_e32 v80, v2
	v_mov_b32_e32 v81, v2
	v_mov_b32_e32 v106, v2
	v_mov_b32_e32 v107, v2
	v_mov_b32_e32 v108, v2
	v_mov_b32_e32 v109, v2
	v_mov_b32_e32 v110, v2
	v_mov_b32_e32 v111, v2
	v_mov_b32_e32 v112, v2
	v_mov_b32_e32 v113, v2
	v_mov_b32_e32 v122, v2
	v_mov_b32_e32 v123, v2
	v_mov_b32_e32 v124, v2
	v_mov_b32_e32 v125, v2
	v_mov_b32_e32 v126, v2
	v_mov_b32_e32 v127, v2
	v_mov_b32_e32 v128, v2
	v_mov_b32_e32 v129, v2
	v_mov_b32_e32 v138, v2
	v_mov_b32_e32 v139, v2
	v_mov_b32_e32 v140, v2
	v_mov_b32_e32 v141, v2
	v_mov_b32_e32 v142, v2
	v_mov_b32_e32 v143, v2
	v_mov_b32_e32 v144, v2
	v_mov_b32_e32 v145, v2
	v_readfirstlane_b32 s98, v146
	s_nop 3
	s_lshr_b32 s98, s98, 6
	s_cmp_ge_u32 s98, 4
	s_cbranch_scc0 .Lgprio1
	s_setprio 1
.Lgprio1:
.LBB0_516:
	s_add_u32 s46, s44, 0xfff80080
	s_addc_u32 s47, s45, -1
	s_add_i32 s58, 0, 0x10000
	s_cmp_eq_u32 s57, 28
	s_cselect_b32 s49, s21, s47
	s_cselect_b32 s48, s50, s46
	s_cselect_b32 s47, s13, s56
	s_cselect_b32 s46, s51, s55
	s_add_i32 s60, 0, 0x14000
	v_add_u32_e32 v102, s58, v172
	v_add_u32_e32 v175, s60, v172
	ds_read_b128 v[82:85], v102
	ds_read_b128 v[86:89], v102 offset:1024
	ds_read_b128 v[98:101], v102 offset:2048
	ds_read_b128 v[102:105], v102 offset:3072
	ds_read_b128 v[154:157], v175
	ds_read_b128 v[168:171], v175 offset:1024
	ds_read_b128 v[176:179], v175 offset:2048
	ds_read_b128 v[180:183], v175 offset:3072
	s_add_i32 m0, s14, 0xc000
	ds_read_b128 v[184:187], v174
	ds_read_b128 v[188:191], v174 offset:1024
	ds_read_b128 v[192:195], v174 offset:2048
	ds_read_b128 v[196:199], v174 offset:3072
	ds_read_b128 v[200:203], v174 offset:4096
	ds_read_b128 v[210:213], v174 offset:5120
	ds_read_b128 v[214:217], v174 offset:6144
	ds_read_b128 v[218:221], v174 offset:7168
	global_load_lds_dwordx4 v164, s[44:45]
	s_add_i32 m0, s14, 0xe000
	s_nop 0
	global_load_lds_dwordx4 v166, s[44:45]
	s_waitcnt vmcnt(8)
	s_waitcnt lgkmcnt(0)
	s_barrier
	s_waitcnt lgkmcnt(0)
	v_mfma_f32_16x16x32_bf16 v[142:145], v[82:85], v[184:187], v[142:145]
	v_mfma_f32_16x16x32_bf16 v[138:141], v[98:101], v[184:187], v[138:141]
	v_mfma_f32_16x16x32_bf16 v[126:129], v[82:85], v[192:195], v[126:129]
	v_mfma_f32_16x16x32_bf16 v[122:125], v[98:101], v[192:195], v[122:125]
	v_mfma_f32_16x16x32_bf16 v[110:113], v[82:85], v[200:203], v[110:113]
	v_mfma_f32_16x16x32_bf16 v[106:109], v[98:101], v[200:203], v[106:109]
	v_mfma_f32_16x16x32_bf16 v[78:81], v[82:85], v[214:217], v[78:81]
	v_mfma_f32_16x16x32_bf16 v[74:77], v[98:101], v[214:217], v[74:77]
	v_mfma_f32_16x16x32_bf16 v[142:145], v[86:89], v[188:191], v[142:145]
	v_mfma_f32_16x16x32_bf16 v[138:141], v[102:105], v[188:191], v[138:141]
	v_mfma_f32_16x16x32_bf16 v[126:129], v[86:89], v[196:199], v[126:129]
	v_mfma_f32_16x16x32_bf16 v[122:125], v[102:105], v[196:199], v[122:125]
	v_mfma_f32_16x16x32_bf16 v[110:113], v[86:89], v[210:213], v[110:113]
	v_mfma_f32_16x16x32_bf16 v[106:109], v[102:105], v[210:213], v[106:109]
	v_mfma_f32_16x16x32_bf16 v[78:81], v[86:89], v[218:221], v[78:81]
	v_mfma_f32_16x16x32_bf16 v[74:77], v[102:105], v[218:221], v[74:77]
	v_mfma_f32_16x16x32_bf16 v[134:137], v[154:157], v[184:187], v[134:137]
	v_mfma_f32_16x16x32_bf16 v[130:133], v[176:179], v[184:187], v[130:133]
	v_mfma_f32_16x16x32_bf16 v[118:121], v[154:157], v[192:195], v[118:121]
	v_mfma_f32_16x16x32_bf16 v[114:117], v[176:179], v[192:195], v[114:117]
	v_mfma_f32_16x16x32_bf16 v[94:97], v[154:157], v[200:203], v[94:97]
	v_mfma_f32_16x16x32_bf16 v[90:93], v[176:179], v[200:203], v[90:93]
	v_mfma_f32_16x16x32_bf16 v[70:73], v[154:157], v[214:217], v[70:73]
	v_mfma_f32_16x16x32_bf16 v[66:69], v[176:179], v[214:217], v[66:69]
	v_mfma_f32_16x16x32_bf16 v[134:137], v[168:171], v[188:191], v[134:137]
	v_mfma_f32_16x16x32_bf16 v[130:133], v[180:183], v[188:191], v[130:133]
	v_mfma_f32_16x16x32_bf16 v[118:121], v[168:171], v[196:199], v[118:121]
	v_mfma_f32_16x16x32_bf16 v[114:117], v[180:183], v[196:199], v[114:117]
	v_mfma_f32_16x16x32_bf16 v[94:97], v[168:171], v[210:213], v[94:97]
	v_mfma_f32_16x16x32_bf16 v[90:93], v[180:183], v[210:213], v[90:93]
	v_mfma_f32_16x16x32_bf16 v[70:73], v[168:171], v[218:221], v[70:73]
	v_mfma_f32_16x16x32_bf16 v[66:69], v[180:183], v[218:221], v[66:69]
	s_barrier
	s_add_i32 s58, s58, s5
	v_lshl_add_u64 v[222:223], s[46:47], 0, v[0:1]
	s_mov_b32 m0, s58
	ds_read_b128 v[184:187], v174 offset:16384
	ds_read_b128 v[188:191], v174 offset:17408
	ds_read_b128 v[192:195], v174 offset:18432
	ds_read_b128 v[196:199], v174 offset:19456
	ds_read_b128 v[200:203], v174 offset:20480
	ds_read_b128 v[210:213], v174 offset:21504
	ds_read_b128 v[214:217], v174 offset:22528
	ds_read_b128 v[218:221], v174 offset:23552
	global_load_lds_dwordx4 v[222:223], off
	s_add_i32 m0, s58, 0x2000
	s_add_u32 s58, s46, 0x80000
	v_lshl_add_u64 v[224:225], s[46:47], 0, v[158:159]
	s_addc_u32 s59, s47, 0
	s_add_i32 s60, s60, s5
	global_load_lds_dwordx4 v[224:225], off
	s_mov_b32 m0, s60
	v_lshl_add_u64 v[228:229], s[48:49], 0, v[160:161]
	global_load_lds_dwordx4 v0, s[58:59]
	s_add_i32 m0, s60, 0x2000
	s_nop 0
	global_load_lds_dwordx4 v158, s[58:59]
	v_lshl_add_u64 v[226:227], s[48:49], 0, v[162:163]
	s_mov_b32 m0, s14
	s_nop 0
	global_load_lds_dwordx4 v[226:227], off
	s_mov_b32 m0, s15
	s_nop 0
	global_load_lds_dwordx4 v[228:229], off
	s_waitcnt vmcnt(8)
	s_waitcnt lgkmcnt(0)
	s_barrier
	s_waitcnt lgkmcnt(0)
	v_mfma_f32_16x16x32_bf16 v[62:65], v[82:85], v[184:187], v[62:65]
	v_mfma_f32_16x16x32_bf16 v[58:61], v[98:101], v[184:187], v[58:61]
	v_mfma_f32_16x16x32_bf16 v[46:49], v[82:85], v[192:195], v[46:49]
	v_mfma_f32_16x16x32_bf16 v[42:45], v[98:101], v[192:195], v[42:45]
	v_mfma_f32_16x16x32_bf16 v[30:33], v[82:85], v[200:203], v[30:33]
	v_mfma_f32_16x16x32_bf16 v[26:29], v[98:101], v[200:203], v[26:29]
	v_mfma_f32_16x16x32_bf16 v[14:17], v[82:85], v[214:217], v[14:17]
	v_mfma_f32_16x16x32_bf16 v[10:13], v[98:101], v[214:217], v[10:13]
	v_mfma_f32_16x16x32_bf16 v[62:65], v[86:89], v[188:191], v[62:65]
	v_mfma_f32_16x16x32_bf16 v[58:61], v[102:105], v[188:191], v[58:61]
	v_mfma_f32_16x16x32_bf16 v[46:49], v[86:89], v[196:199], v[46:49]
	v_mfma_f32_16x16x32_bf16 v[42:45], v[102:105], v[196:199], v[42:45]
	v_mfma_f32_16x16x32_bf16 v[30:33], v[86:89], v[210:213], v[30:33]
	v_mfma_f32_16x16x32_bf16 v[26:29], v[102:105], v[210:213], v[26:29]
	v_mfma_f32_16x16x32_bf16 v[14:17], v[86:89], v[218:221], v[14:17]
	v_mfma_f32_16x16x32_bf16 v[10:13], v[102:105], v[218:221], v[10:13]
	v_mfma_f32_16x16x32_bf16 v[54:57], v[154:157], v[184:187], v[54:57]
	v_mfma_f32_16x16x32_bf16 v[50:53], v[176:179], v[184:187], v[50:53]
	v_mfma_f32_16x16x32_bf16 v[38:41], v[154:157], v[192:195], v[38:41]
	v_mfma_f32_16x16x32_bf16 v[34:37], v[176:179], v[192:195], v[34:37]
	v_mfma_f32_16x16x32_bf16 v[22:25], v[154:157], v[200:203], v[22:25]
	v_mfma_f32_16x16x32_bf16 v[18:21], v[176:179], v[200:203], v[18:21]
	v_mfma_f32_16x16x32_bf16 v[6:9], v[154:157], v[214:217], v[6:9]
	v_mfma_f32_16x16x32_bf16 v[2:5], v[176:179], v[214:217], v[2:5]
	v_mfma_f32_16x16x32_bf16 v[54:57], v[168:171], v[188:191], v[54:57]
	v_mfma_f32_16x16x32_bf16 v[50:53], v[180:183], v[188:191], v[50:53]
	v_mfma_f32_16x16x32_bf16 v[38:41], v[168:171], v[196:199], v[38:41]
	v_mfma_f32_16x16x32_bf16 v[34:37], v[180:183], v[196:199], v[34:37]
	v_mfma_f32_16x16x32_bf16 v[22:25], v[168:171], v[210:213], v[22:25]
	v_mfma_f32_16x16x32_bf16 v[18:21], v[180:183], v[210:213], v[18:21]
	v_mfma_f32_16x16x32_bf16 v[6:9], v[168:171], v[218:221], v[6:9]
	v_mfma_f32_16x16x32_bf16 v[2:5], v[180:183], v[218:221], v[2:5]
	s_barrier
	s_add_i32 s58, 0, 0x18000
	s_add_i32 s59, 0, 0x1c000
	v_add_u32_e32 v102, s58, v172
	v_add_u32_e32 v175, s59, v172
	ds_read_b128 v[82:85], v102
	ds_read_b128 v[86:89], v102 offset:1024
	ds_read_b128 v[98:101], v102 offset:2048
	ds_read_b128 v[102:105], v102 offset:3072
	ds_read_b128 v[154:157], v175
	ds_read_b128 v[168:171], v175 offset:1024
	ds_read_b128 v[176:179], v175 offset:2048
	ds_read_b128 v[180:183], v175 offset:3072
	s_add_u32 s48, s48, 0x80000
	s_addc_u32 s49, s49, 0
	s_mov_b32 m0, s16
	ds_read_b128 v[184:187], v174 offset:32768
	ds_read_b128 v[188:191], v174 offset:33792
	ds_read_b128 v[192:195], v174 offset:34816
	ds_read_b128 v[196:199], v174 offset:35840
	ds_read_b128 v[200:203], v174 offset:36864
	ds_read_b128 v[210:213], v174 offset:37888
	ds_read_b128 v[214:217], v174 offset:38912
	ds_read_b128 v[218:221], v174 offset:39936
	global_load_lds_dwordx4 v162, s[48:49]
	s_mov_b32 m0, s18
	s_nop 0
	global_load_lds_dwordx4 v160, s[48:49]
	s_waitcnt vmcnt(8)
	s_waitcnt lgkmcnt(0)
	s_barrier
	s_waitcnt lgkmcnt(0)
	v_mfma_f32_16x16x32_bf16 v[142:145], v[82:85], v[184:187], v[142:145]
	v_mfma_f32_16x16x32_bf16 v[138:141], v[98:101], v[184:187], v[138:141]
	v_mfma_f32_16x16x32_bf16 v[126:129], v[82:85], v[192:195], v[126:129]
	v_mfma_f32_16x16x32_bf16 v[122:125], v[98:101], v[192:195], v[122:125]
	v_mfma_f32_16x16x32_bf16 v[110:113], v[82:85], v[200:203], v[110:113]
	v_mfma_f32_16x16x32_bf16 v[106:109], v[98:101], v[200:203], v[106:109]
	v_mfma_f32_16x16x32_bf16 v[78:81], v[82:85], v[214:217], v[78:81]
	v_mfma_f32_16x16x32_bf16 v[74:77], v[98:101], v[214:217], v[74:77]
	v_mfma_f32_16x16x32_bf16 v[142:145], v[86:89], v[188:191], v[142:145]
	v_mfma_f32_16x16x32_bf16 v[138:141], v[102:105], v[188:191], v[138:141]
	v_mfma_f32_16x16x32_bf16 v[126:129], v[86:89], v[196:199], v[126:129]
	v_mfma_f32_16x16x32_bf16 v[122:125], v[102:105], v[196:199], v[122:125]
	v_mfma_f32_16x16x32_bf16 v[110:113], v[86:89], v[210:213], v[110:113]
	v_mfma_f32_16x16x32_bf16 v[106:109], v[102:105], v[210:213], v[106:109]
	v_mfma_f32_16x16x32_bf16 v[78:81], v[86:89], v[218:221], v[78:81]
	v_mfma_f32_16x16x32_bf16 v[74:77], v[102:105], v[218:221], v[74:77]
	v_mfma_f32_16x16x32_bf16 v[134:137], v[154:157], v[184:187], v[134:137]
	v_mfma_f32_16x16x32_bf16 v[130:133], v[176:179], v[184:187], v[130:133]
	v_mfma_f32_16x16x32_bf16 v[118:121], v[154:157], v[192:195], v[118:121]
	v_mfma_f32_16x16x32_bf16 v[114:117], v[176:179], v[192:195], v[114:117]
	v_mfma_f32_16x16x32_bf16 v[94:97], v[154:157], v[200:203], v[94:97]
	v_mfma_f32_16x16x32_bf16 v[90:93], v[176:179], v[200:203], v[90:93]
	v_mfma_f32_16x16x32_bf16 v[70:73], v[154:157], v[214:217], v[70:73]
	v_mfma_f32_16x16x32_bf16 v[66:69], v[176:179], v[214:217], v[66:69]
	v_mfma_f32_16x16x32_bf16 v[134:137], v[168:171], v[188:191], v[134:137]
	v_mfma_f32_16x16x32_bf16 v[130:133], v[180:183], v[188:191], v[130:133]
	v_mfma_f32_16x16x32_bf16 v[118:121], v[168:171], v[196:199], v[118:121]
	v_mfma_f32_16x16x32_bf16 v[114:117], v[180:183], v[196:199], v[114:117]
	v_mfma_f32_16x16x32_bf16 v[94:97], v[168:171], v[210:213], v[94:97]
	v_mfma_f32_16x16x32_bf16 v[90:93], v[180:183], v[210:213], v[90:93]
	v_mfma_f32_16x16x32_bf16 v[70:73], v[168:171], v[218:221], v[70:73]
	v_mfma_f32_16x16x32_bf16 v[66:69], v[180:183], v[218:221], v[66:69]
	s_barrier
	s_add_i32 s48, s58, s5
	v_lshl_add_u64 v[222:223], v[222:223], 0, s[34:35]
	s_mov_b32 m0, s48
	ds_read_b128 v[184:187], v174 offset:49152
	ds_read_b128 v[188:191], v174 offset:50176
	ds_read_b128 v[192:195], v174 offset:51200
	ds_read_b128 v[196:199], v174 offset:52224
	ds_read_b128 v[200:203], v174 offset:53248
	ds_read_b128 v[210:213], v174 offset:54272
	ds_read_b128 v[214:217], v174 offset:55296
	ds_read_b128 v[218:221], v174 offset:56320
	global_load_lds_dwordx4 v[222:223], off
	s_add_i32 m0, s48, 0x2000
	s_add_u32 s46, s46, 0x80080
	v_lshl_add_u64 v[222:223], v[224:225], 0, s[34:35]
	s_addc_u32 s47, s47, 0
	s_add_i32 s48, s59, s5
	global_load_lds_dwordx4 v[222:223], off
	s_mov_b32 m0, s48
	s_nop 0
	global_load_lds_dwordx4 v0, s[46:47]
	s_add_i32 m0, s48, 0x2000
	s_nop 0
	global_load_lds_dwordx4 v158, s[46:47]
	v_lshl_add_u64 v[222:223], v[226:227], 0, s[34:35]
	s_mov_b32 m0, s25
	s_nop 0
	global_load_lds_dwordx4 v[222:223], off
	v_lshl_add_u64 v[222:223], v[228:229], 0, s[34:35]
	s_mov_b32 m0, s33
	s_nop 0
	global_load_lds_dwordx4 v[222:223], off
	s_waitcnt vmcnt(8)
	s_waitcnt lgkmcnt(0)
	s_barrier
	s_waitcnt lgkmcnt(0)
	v_mfma_f32_16x16x32_bf16 v[62:65], v[82:85], v[184:187], v[62:65]
	v_mfma_f32_16x16x32_bf16 v[58:61], v[98:101], v[184:187], v[58:61]
	v_mfma_f32_16x16x32_bf16 v[46:49], v[82:85], v[192:195], v[46:49]
	v_mfma_f32_16x16x32_bf16 v[42:45], v[98:101], v[192:195], v[42:45]
	v_mfma_f32_16x16x32_bf16 v[30:33], v[82:85], v[200:203], v[30:33]
	v_mfma_f32_16x16x32_bf16 v[26:29], v[98:101], v[200:203], v[26:29]
	v_mfma_f32_16x16x32_bf16 v[14:17], v[82:85], v[214:217], v[14:17]
	v_mfma_f32_16x16x32_bf16 v[10:13], v[98:101], v[214:217], v[10:13]
	v_mfma_f32_16x16x32_bf16 v[62:65], v[86:89], v[188:191], v[62:65]
	v_mfma_f32_16x16x32_bf16 v[58:61], v[102:105], v[188:191], v[58:61]
	v_mfma_f32_16x16x32_bf16 v[46:49], v[86:89], v[196:199], v[46:49]
	v_mfma_f32_16x16x32_bf16 v[42:45], v[102:105], v[196:199], v[42:45]
	v_mfma_f32_16x16x32_bf16 v[30:33], v[86:89], v[210:213], v[30:33]
	v_mfma_f32_16x16x32_bf16 v[26:29], v[102:105], v[210:213], v[26:29]
	v_mfma_f32_16x16x32_bf16 v[14:17], v[86:89], v[218:221], v[14:17]
	v_mfma_f32_16x16x32_bf16 v[10:13], v[102:105], v[218:221], v[10:13]
	v_mfma_f32_16x16x32_bf16 v[54:57], v[154:157], v[184:187], v[54:57]
	v_mfma_f32_16x16x32_bf16 v[50:53], v[176:179], v[184:187], v[50:53]
	v_mfma_f32_16x16x32_bf16 v[38:41], v[154:157], v[192:195], v[38:41]
	v_mfma_f32_16x16x32_bf16 v[34:37], v[176:179], v[192:195], v[34:37]
	v_mfma_f32_16x16x32_bf16 v[22:25], v[154:157], v[200:203], v[22:25]
	v_mfma_f32_16x16x32_bf16 v[18:21], v[176:179], v[200:203], v[18:21]
	v_mfma_f32_16x16x32_bf16 v[6:9], v[154:157], v[214:217], v[6:9]
	v_mfma_f32_16x16x32_bf16 v[2:5], v[176:179], v[214:217], v[2:5]
	v_mfma_f32_16x16x32_bf16 v[54:57], v[168:171], v[188:191], v[54:57]
	v_mfma_f32_16x16x32_bf16 v[50:53], v[180:183], v[188:191], v[50:53]
	v_mfma_f32_16x16x32_bf16 v[38:41], v[168:171], v[196:199], v[38:41]
	v_mfma_f32_16x16x32_bf16 v[34:37], v[180:183], v[196:199], v[34:37]
	v_mfma_f32_16x16x32_bf16 v[22:25], v[168:171], v[210:213], v[22:25]
	v_mfma_f32_16x16x32_bf16 v[18:21], v[180:183], v[210:213], v[18:21]
	v_mfma_f32_16x16x32_bf16 v[6:9], v[168:171], v[218:221], v[6:9]
	v_mfma_f32_16x16x32_bf16 v[2:5], v[180:183], v[218:221], v[2:5]
	s_barrier
	s_add_i32 s57, s57, 2
	s_add_u32 s44, s44, 0x100
	s_addc_u32 s45, s45, 0
	s_add_u32 s55, s55, 0x100
	s_addc_u32 s56, s56, 0
	s_cmp_gt_u32 s57, 29
	s_cbranch_scc0 .LBB0_516
	s_setprio 0
	s_and_b64 vcc, exec, s[10:11]
	s_cbranch_vccz .LBB0_519
	s_barrier

.LBB0_603:
	s_ashr_i32 s41, s40, 31
	s_lshl_b64 s[18:19], s[40:41], 20
	s_add_u32 s42, s0, s18
	s_addc_u32 s43, s1, s19
	s_and_b64 s[18:19], s[38:39], exec
	s_cselect_b32 s18, s43, s7
	s_cselect_b32 s19, s42, s6
	s_ashr_i32 s21, s20, 31
	s_lshl_b64 s[44:45], s[20:21], 20
	s_add_u32 s44, s2, s44
	s_addc_u32 s45, s14, s45
	s_and_b64 s[46:47], s[38:39], exec
	s_cselect_b32 s21, s45, s23
	s_cselect_b32 s25, s44, s22
	s_add_u32 s6, s6, 0x80080
	s_addc_u32 s7, s7, 0
	s_add_u32 s41, s22, 0x100
	v_mov_b32_e32 v2, 0
	s_addc_u32 s52, s23, 0
	s_mov_b32 s53, -2
	v_mov_b32_e32 v3, v2
	v_mov_b32_e32 v4, v2
	v_mov_b32_e32 v5, v2
	v_mov_b32_e32 v6, v2
	v_mov_b32_e32 v7, v2
	v_mov_b32_e32 v8, v2
	v_mov_b32_e32 v9, v2
	v_mov_b32_e32 v18, v2
	v_mov_b32_e32 v19, v2
	v_mov_b32_e32 v20, v2
	v_mov_b32_e32 v21, v2
	v_mov_b32_e32 v22, v2
	v_mov_b32_e32 v23, v2
	v_mov_b32_e32 v24, v2
	v_mov_b32_e32 v25, v2
	v_mov_b32_e32 v34, v2
	v_mov_b32_e32 v35, v2
	v_mov_b32_e32 v36, v2
	v_mov_b32_e32 v37, v2
	v_mov_b32_e32 v38, v2
	v_mov_b32_e32 v39, v2
	v_mov_b32_e32 v40, v2
	v_mov_b32_e32 v41, v2
	v_mov_b32_e32 v50, v2
	v_mov_b32_e32 v51, v2
	v_mov_b32_e32 v52, v2
	v_mov_b32_e32 v53, v2
	v_mov_b32_e32 v54, v2
	v_mov_b32_e32 v55, v2
	v_mov_b32_e32 v56, v2
	v_mov_b32_e32 v57, v2
	v_mov_b32_e32 v10, v2
	v_mov_b32_e32 v11, v2
	v_mov_b32_e32 v12, v2
	v_mov_b32_e32 v13, v2
	v_mov_b32_e32 v14, v2
	v_mov_b32_e32 v15, v2
	v_mov_b32_e32 v16, v2
	v_mov_b32_e32 v17, v2
	v_mov_b32_e32 v26, v2
	v_mov_b32_e32 v27, v2
	v_mov_b32_e32 v28, v2
	v_mov_b32_e32 v29, v2
	v_mov_b32_e32 v30, v2
	v_mov_b32_e32 v31, v2
	v_mov_b32_e32 v32, v2
	v_mov_b32_e32 v33, v2
	v_mov_b32_e32 v42, v2
	v_mov_b32_e32 v43, v2
	v_mov_b32_e32 v44, v2
	v_mov_b32_e32 v45, v2
	v_mov_b32_e32 v46, v2
	v_mov_b32_e32 v47, v2
	v_mov_b32_e32 v48, v2
	v_mov_b32_e32 v49, v2
	v_mov_b32_e32 v58, v2
	v_mov_b32_e32 v59, v2
	v_mov_b32_e32 v60, v2
	v_mov_b32_e32 v61, v2
	v_mov_b32_e32 v62, v2
	v_mov_b32_e32 v63, v2
	v_mov_b32_e32 v64, v2
	v_mov_b32_e32 v65, v2
	v_mov_b32_e32 v66, v2
	v_mov_b32_e32 v67, v2
	v_mov_b32_e32 v68, v2
	v_mov_b32_e32 v69, v2
	v_mov_b32_e32 v70, v2
	v_mov_b32_e32 v71, v2
	v_mov_b32_e32 v72, v2
	v_mov_b32_e32 v73, v2
	v_mov_b32_e32 v82, v2
	v_mov_b32_e32 v83, v2
	v_mov_b32_e32 v84, v2
	v_mov_b32_e32 v85, v2
	v_mov_b32_e32 v86, v2
	v_mov_b32_e32 v87, v2
	v_mov_b32_e32 v88, v2
	v_mov_b32_e32 v89, v2
	v_mov_b32_e32 v98, v2
	v_mov_b32_e32 v99, v2
	v_mov_b32_e32 v100, v2
	v_mov_b32_e32 v101, v2
	v_mov_b32_e32 v102, v2
	v_mov_b32_e32 v103, v2
	v_mov_b32_e32 v104, v2
	v_mov_b32_e32 v105, v2
	v_mov_b32_e32 v114, v2
	v_mov_b32_e32 v115, v2
	v_mov_b32_e32 v116, v2
	v_mov_b32_e32 v117, v2
	v_mov_b32_e32 v118, v2
	v_mov_b32_e32 v119, v2
	v_mov_b32_e32 v120, v2
	v_mov_b32_e32 v121, v2
	v_mov_b32_e32 v74, v2
	v_mov_b32_e32 v75, v2
	v_mov_b32_e32 v76, v2
	v_mov_b32_e32 v77, v2
	v_mov_b32_e32 v78, v2
	v_mov_b32_e32 v79, v2
	v_mov_b32_e32 v80, v2
	v_mov_b32_e32 v81, v2
	v_mov_b32_e32 v90, v2
	v_mov_b32_e32 v91, v2
	v_mov_b32_e32 v92, v2
	v_mov_b32_e32 v93, v2
	v_mov_b32_e32 v94, v2
	v_mov_b32_e32 v95, v2
	v_mov_b32_e32 v96, v2
	v_mov_b32_e32 v97, v2
	v_mov_b32_e32 v106, v2
	v_mov_b32_e32 v107, v2
	v_mov_b32_e32 v108, v2
	v_mov_b32_e32 v109, v2
	v_mov_b32_e32 v110, v2
	v_mov_b32_e32 v111, v2
	v_mov_b32_e32 v112, v2
	v_mov_b32_e32 v113, v2
	v_mov_b32_e32 v122, v2
	v_mov_b32_e32 v123, v2
	v_mov_b32_e32 v124, v2
	v_mov_b32_e32 v125, v2
	v_mov_b32_e32 v126, v2
	v_mov_b32_e32 v127, v2
	v_mov_b32_e32 v128, v2
	v_mov_b32_e32 v129, v2
	v_readfirstlane_b32 s98, v146
	s_nop 3
	s_lshr_b32 s98, s98, 6
	s_cmp_ge_u32 s98, 4
	s_cbranch_scc0 .Lgprio2
	s_setprio 1
.Lgprio2:
.LBB0_604:
	s_add_u32 s22, s6, 0xfff80080
	s_addc_u32 s23, s7, -1
	s_add_i32 s54, 0, 0x10000
	s_cmp_eq_u32 s53, 28
	s_cselect_b32 s47, s18, s23
	s_cselect_b32 s46, s19, s22
	s_cselect_b32 s23, s21, s52
	s_cselect_b32 s22, s25, s41
	s_add_i32 s56, 0, 0x14000
	v_add_u32_e32 v162, s54, v175
	v_add_u32_e32 v174, s56, v175
	ds_read_b128 v[130:133], v162
	ds_read_b128 v[134:137], v162 offset:1024
	ds_read_b128 v[154:157], v162 offset:2048
	ds_read_b128 v[162:165], v162 offset:3072
	ds_read_b128 v[166:169], v174
	ds_read_b128 v[170:173], v174 offset:1024
	ds_read_b128 v[180:183], v174 offset:2048
	ds_read_b128 v[184:187], v174 offset:3072
	s_add_i32 m0, s16, 0xc000
	ds_read_b128 v[188:191], v179
	ds_read_b128 v[192:195], v179 offset:1024
	ds_read_b128 v[196:199], v179 offset:2048
	ds_read_b128 v[200:203], v179 offset:3072
	ds_read_b128 v[210:213], v179 offset:4096
	ds_read_b128 v[214:217], v179 offset:5120
	ds_read_b128 v[218:221], v179 offset:6144
	ds_read_b128 v[222:225], v179 offset:7168
	global_load_lds_dwordx4 v158, s[6:7]
	s_add_i32 m0, s16, 0xe000
	s_nop 0
	global_load_lds_dwordx4 v160, s[6:7]
	s_waitcnt vmcnt(8)
	s_waitcnt lgkmcnt(0)
	s_barrier
	s_waitcnt lgkmcnt(0)
	v_mfma_f32_16x16x32_bf16 v[126:129], v[130:133], v[188:191], v[126:129]
	v_mfma_f32_16x16x32_bf16 v[122:125], v[154:157], v[188:191], v[122:125]
	v_mfma_f32_16x16x32_bf16 v[110:113], v[130:133], v[196:199], v[110:113]
	v_mfma_f32_16x16x32_bf16 v[106:109], v[154:157], v[196:199], v[106:109]
	v_mfma_f32_16x16x32_bf16 v[94:97], v[130:133], v[210:213], v[94:97]
	v_mfma_f32_16x16x32_bf16 v[90:93], v[154:157], v[210:213], v[90:93]
	v_mfma_f32_16x16x32_bf16 v[78:81], v[130:133], v[218:221], v[78:81]
	v_mfma_f32_16x16x32_bf16 v[74:77], v[154:157], v[218:221], v[74:77]
	v_mfma_f32_16x16x32_bf16 v[126:129], v[134:137], v[192:195], v[126:129]
	v_mfma_f32_16x16x32_bf16 v[122:125], v[162:165], v[192:195], v[122:125]
	v_mfma_f32_16x16x32_bf16 v[110:113], v[134:137], v[200:203], v[110:113]
	v_mfma_f32_16x16x32_bf16 v[106:109], v[162:165], v[200:203], v[106:109]
	v_mfma_f32_16x16x32_bf16 v[94:97], v[134:137], v[214:217], v[94:97]
	v_mfma_f32_16x16x32_bf16 v[90:93], v[162:165], v[214:217], v[90:93]
	v_mfma_f32_16x16x32_bf16 v[78:81], v[134:137], v[222:225], v[78:81]
	v_mfma_f32_16x16x32_bf16 v[74:77], v[162:165], v[222:225], v[74:77]
	v_mfma_f32_16x16x32_bf16 v[118:121], v[166:169], v[188:191], v[118:121]
	v_mfma_f32_16x16x32_bf16 v[114:117], v[180:183], v[188:191], v[114:117]
	v_mfma_f32_16x16x32_bf16 v[102:105], v[166:169], v[196:199], v[102:105]
	v_mfma_f32_16x16x32_bf16 v[98:101], v[180:183], v[196:199], v[98:101]
	v_mfma_f32_16x16x32_bf16 v[86:89], v[166:169], v[210:213], v[86:89]
	v_mfma_f32_16x16x32_bf16 v[82:85], v[180:183], v[210:213], v[82:85]
	v_mfma_f32_16x16x32_bf16 v[70:73], v[166:169], v[218:221], v[70:73]
	v_mfma_f32_16x16x32_bf16 v[66:69], v[180:183], v[218:221], v[66:69]
	v_mfma_f32_16x16x32_bf16 v[118:121], v[170:173], v[192:195], v[118:121]
	v_mfma_f32_16x16x32_bf16 v[114:117], v[184:187], v[192:195], v[114:117]
	v_mfma_f32_16x16x32_bf16 v[102:105], v[170:173], v[200:203], v[102:105]
	v_mfma_f32_16x16x32_bf16 v[98:101], v[184:187], v[200:203], v[98:101]
	v_mfma_f32_16x16x32_bf16 v[86:89], v[170:173], v[214:217], v[86:89]
	v_mfma_f32_16x16x32_bf16 v[82:85], v[184:187], v[214:217], v[82:85]
	v_mfma_f32_16x16x32_bf16 v[70:73], v[170:173], v[222:225], v[70:73]
	v_mfma_f32_16x16x32_bf16 v[66:69], v[184:187], v[222:225], v[66:69]
	s_barrier
	s_add_i32 s54, s54, s15
	v_lshl_add_u64 v[226:227], s[22:23], 0, v[142:143]
	s_mov_b32 m0, s54
	ds_read_b128 v[188:191], v179 offset:16384
	ds_read_b128 v[192:195], v179 offset:17408
	ds_read_b128 v[196:199], v179 offset:18432
	ds_read_b128 v[200:203], v179 offset:19456
	ds_read_b128 v[210:213], v179 offset:20480
	ds_read_b128 v[214:217], v179 offset:21504
	ds_read_b128 v[218:221], v179 offset:22528
	ds_read_b128 v[222:225], v179 offset:23552
	global_load_lds_dwordx4 v[226:227], off
	s_add_i32 m0, s54, 0x2000
	s_add_u32 s54, s22, 0x80000
	v_lshl_add_u64 v[228:229], s[22:23], 0, v[138:139]
	s_addc_u32 s55, s23, 0
	s_add_i32 s56, s56, s15
	global_load_lds_dwordx4 v[228:229], off
	s_mov_b32 m0, s56
	v_lshl_add_u64 v[232:233], s[46:47], 0, v[140:141]
	global_load_lds_dwordx4 v142, s[54:55]
	s_add_i32 m0, s56, 0x2000
	s_nop 0
	global_load_lds_dwordx4 v138, s[54:55]
	v_lshl_add_u64 v[230:231], s[46:47], 0, v[144:145]
	s_mov_b32 m0, s16
	s_nop 0
	global_load_lds_dwordx4 v[230:231], off
	s_mov_b32 m0, s33
	s_nop 0
	global_load_lds_dwordx4 v[232:233], off
	s_waitcnt vmcnt(8)
	s_waitcnt lgkmcnt(0)
	s_barrier
	s_waitcnt lgkmcnt(0)
	v_mfma_f32_16x16x32_bf16 v[62:65], v[130:133], v[188:191], v[62:65]
	v_mfma_f32_16x16x32_bf16 v[58:61], v[154:157], v[188:191], v[58:61]
	v_mfma_f32_16x16x32_bf16 v[46:49], v[130:133], v[196:199], v[46:49]
	v_mfma_f32_16x16x32_bf16 v[42:45], v[154:157], v[196:199], v[42:45]
	v_mfma_f32_16x16x32_bf16 v[30:33], v[130:133], v[210:213], v[30:33]
	v_mfma_f32_16x16x32_bf16 v[26:29], v[154:157], v[210:213], v[26:29]
	v_mfma_f32_16x16x32_bf16 v[14:17], v[130:133], v[218:221], v[14:17]
	v_mfma_f32_16x16x32_bf16 v[10:13], v[154:157], v[218:221], v[10:13]
	v_mfma_f32_16x16x32_bf16 v[62:65], v[134:137], v[192:195], v[62:65]
	v_mfma_f32_16x16x32_bf16 v[58:61], v[162:165], v[192:195], v[58:61]
	v_mfma_f32_16x16x32_bf16 v[46:49], v[134:137], v[200:203], v[46:49]
	v_mfma_f32_16x16x32_bf16 v[42:45], v[162:165], v[200:203], v[42:45]
	v_mfma_f32_16x16x32_bf16 v[30:33], v[134:137], v[214:217], v[30:33]
	v_mfma_f32_16x16x32_bf16 v[26:29], v[162:165], v[214:217], v[26:29]
	v_mfma_f32_16x16x32_bf16 v[14:17], v[134:137], v[222:225], v[14:17]
	v_mfma_f32_16x16x32_bf16 v[10:13], v[162:165], v[222:225], v[10:13]
	v_mfma_f32_16x16x32_bf16 v[54:57], v[166:169], v[188:191], v[54:57]
	v_mfma_f32_16x16x32_bf16 v[50:53], v[180:183], v[188:191], v[50:53]
	v_mfma_f32_16x16x32_bf16 v[38:41], v[166:169], v[196:199], v[38:41]
	v_mfma_f32_16x16x32_bf16 v[34:37], v[180:183], v[196:199], v[34:37]
	v_mfma_f32_16x16x32_bf16 v[22:25], v[166:169], v[210:213], v[22:25]
	v_mfma_f32_16x16x32_bf16 v[18:21], v[180:183], v[210:213], v[18:21]
	v_mfma_f32_16x16x32_bf16 v[6:9], v[166:169], v[218:221], v[6:9]
	v_mfma_f32_16x16x32_bf16 v[2:5], v[180:183], v[218:221], v[2:5]
	v_mfma_f32_16x16x32_bf16 v[54:57], v[170:173], v[192:195], v[54:57]
	v_mfma_f32_16x16x32_bf16 v[50:53], v[184:187], v[192:195], v[50:53]
	v_mfma_f32_16x16x32_bf16 v[38:41], v[170:173], v[200:203], v[38:41]
	v_mfma_f32_16x16x32_bf16 v[34:37], v[184:187], v[200:203], v[34:37]
	v_mfma_f32_16x16x32_bf16 v[22:25], v[170:173], v[214:217], v[22:25]
	v_mfma_f32_16x16x32_bf16 v[18:21], v[184:187], v[214:217], v[18:21]
	v_mfma_f32_16x16x32_bf16 v[6:9], v[170:173], v[222:225], v[6:9]
	v_mfma_f32_16x16x32_bf16 v[2:5], v[184:187], v[222:225], v[2:5]
	s_barrier
	s_add_i32 s54, 0, 0x18000
	s_add_i32 s55, 0, 0x1c000
	v_add_u32_e32 v162, s54, v175
	v_add_u32_e32 v174, s55, v175
	ds_read_b128 v[130:133], v162
	ds_read_b128 v[134:137], v162 offset:1024
	ds_read_b128 v[154:157], v162 offset:2048
	ds_read_b128 v[162:165], v162 offset:3072
	ds_read_b128 v[166:169], v174
	ds_read_b128 v[170:173], v174 offset:1024
	ds_read_b128 v[180:183], v174 offset:2048
	ds_read_b128 v[184:187], v174 offset:3072
	s_add_u32 s46, s46, 0x80000
	s_addc_u32 s47, s47, 0
	s_mov_b32 m0, s37
	ds_read_b128 v[188:191], v179 offset:32768
	ds_read_b128 v[192:195], v179 offset:33792
	ds_read_b128 v[196:199], v179 offset:34816
	ds_read_b128 v[200:203], v179 offset:35840
	ds_read_b128 v[210:213], v179 offset:36864
	ds_read_b128 v[214:217], v179 offset:37888
	ds_read_b128 v[218:221], v179 offset:38912
	ds_read_b128 v[222:225], v179 offset:39936
	global_load_lds_dwordx4 v144, s[46:47]
	s_mov_b32 m0, s48
	s_nop 0
	global_load_lds_dwordx4 v140, s[46:47]
	s_waitcnt vmcnt(8)
	s_waitcnt lgkmcnt(0)
	s_barrier
	s_waitcnt lgkmcnt(0)
	v_mfma_f32_16x16x32_bf16 v[126:129], v[130:133], v[188:191], v[126:129]
	v_mfma_f32_16x16x32_bf16 v[122:125], v[154:157], v[188:191], v[122:125]
	v_mfma_f32_16x16x32_bf16 v[110:113], v[130:133], v[196:199], v[110:113]
	v_mfma_f32_16x16x32_bf16 v[106:109], v[154:157], v[196:199], v[106:109]
	v_mfma_f32_16x16x32_bf16 v[94:97], v[130:133], v[210:213], v[94:97]
	v_mfma_f32_16x16x32_bf16 v[90:93], v[154:157], v[210:213], v[90:93]
	v_mfma_f32_16x16x32_bf16 v[78:81], v[130:133], v[218:221], v[78:81]
	v_mfma_f32_16x16x32_bf16 v[74:77], v[154:157], v[218:221], v[74:77]
	v_mfma_f32_16x16x32_bf16 v[126:129], v[134:137], v[192:195], v[126:129]
	v_mfma_f32_16x16x32_bf16 v[122:125], v[162:165], v[192:195], v[122:125]
	v_mfma_f32_16x16x32_bf16 v[110:113], v[134:137], v[200:203], v[110:113]
	v_mfma_f32_16x16x32_bf16 v[106:109], v[162:165], v[200:203], v[106:109]
	v_mfma_f32_16x16x32_bf16 v[94:97], v[134:137], v[214:217], v[94:97]
	v_mfma_f32_16x16x32_bf16 v[90:93], v[162:165], v[214:217], v[90:93]
	v_mfma_f32_16x16x32_bf16 v[78:81], v[134:137], v[222:225], v[78:81]
	v_mfma_f32_16x16x32_bf16 v[74:77], v[162:165], v[222:225], v[74:77]
	v_mfma_f32_16x16x32_bf16 v[118:121], v[166:169], v[188:191], v[118:121]
	v_mfma_f32_16x16x32_bf16 v[114:117], v[180:183], v[188:191], v[114:117]
	v_mfma_f32_16x16x32_bf16 v[102:105], v[166:169], v[196:199], v[102:105]
	v_mfma_f32_16x16x32_bf16 v[98:101], v[180:183], v[196:199], v[98:101]
	v_mfma_f32_16x16x32_bf16 v[86:89], v[166:169], v[210:213], v[86:89]
	v_mfma_f32_16x16x32_bf16 v[82:85], v[180:183], v[210:213], v[82:85]
	v_mfma_f32_16x16x32_bf16 v[70:73], v[166:169], v[218:221], v[70:73]
	v_mfma_f32_16x16x32_bf16 v[66:69], v[180:183], v[218:221], v[66:69]
	v_mfma_f32_16x16x32_bf16 v[118:121], v[170:173], v[192:195], v[118:121]
	v_mfma_f32_16x16x32_bf16 v[114:117], v[184:187], v[192:195], v[114:117]
	v_mfma_f32_16x16x32_bf16 v[102:105], v[170:173], v[200:203], v[102:105]
	v_mfma_f32_16x16x32_bf16 v[98:101], v[184:187], v[200:203], v[98:101]
	v_mfma_f32_16x16x32_bf16 v[86:89], v[170:173], v[214:217], v[86:89]
	v_mfma_f32_16x16x32_bf16 v[82:85], v[184:187], v[214:217], v[82:85]
	v_mfma_f32_16x16x32_bf16 v[70:73], v[170:173], v[222:225], v[70:73]
	v_mfma_f32_16x16x32_bf16 v[66:69], v[184:187], v[222:225], v[66:69]
	s_barrier
	s_add_i32 s46, s54, s15
	v_lshl_add_u64 v[226:227], v[226:227], 0, s[34:35]
	s_mov_b32 m0, s46
	ds_read_b128 v[188:191], v179 offset:49152
	ds_read_b128 v[192:195], v179 offset:50176
	ds_read_b128 v[196:199], v179 offset:51200
	ds_read_b128 v[200:203], v179 offset:52224
	ds_read_b128 v[210:213], v179 offset:53248
	ds_read_b128 v[214:217], v179 offset:54272
	ds_read_b128 v[218:221], v179 offset:55296
	ds_read_b128 v[222:225], v179 offset:56320
	global_load_lds_dwordx4 v[226:227], off
	s_add_i32 m0, s46, 0x2000
	s_add_u32 s22, s22, 0x80080
	v_lshl_add_u64 v[226:227], v[228:229], 0, s[34:35]
	s_addc_u32 s23, s23, 0
	s_add_i32 s46, s55, s15
	global_load_lds_dwordx4 v[226:227], off
	s_mov_b32 m0, s46
	s_nop 0
	global_load_lds_dwordx4 v142, s[22:23]
	s_add_i32 m0, s46, 0x2000
	s_nop 0
	global_load_lds_dwordx4 v138, s[22:23]
	v_lshl_add_u64 v[226:227], v[230:231], 0, s[34:35]
	s_mov_b32 m0, s49
	s_nop 0
	global_load_lds_dwordx4 v[226:227], off
	v_lshl_add_u64 v[226:227], v[232:233], 0, s[34:35]
	s_mov_b32 m0, s50
	s_nop 0
	global_load_lds_dwordx4 v[226:227], off
	s_waitcnt vmcnt(8)
	s_waitcnt lgkmcnt(0)
	s_barrier
	s_waitcnt lgkmcnt(0)
	v_mfma_f32_16x16x32_bf16 v[62:65], v[130:133], v[188:191], v[62:65]
	v_mfma_f32_16x16x32_bf16 v[58:61], v[154:157], v[188:191], v[58:61]
	v_mfma_f32_16x16x32_bf16 v[46:49], v[130:133], v[196:199], v[46:49]
	v_mfma_f32_16x16x32_bf16 v[42:45], v[154:157], v[196:199], v[42:45]
	v_mfma_f32_16x16x32_bf16 v[30:33], v[130:133], v[210:213], v[30:33]
	v_mfma_f32_16x16x32_bf16 v[26:29], v[154:157], v[210:213], v[26:29]
	v_mfma_f32_16x16x32_bf16 v[14:17], v[130:133], v[218:221], v[14:17]
	v_mfma_f32_16x16x32_bf16 v[10:13], v[154:157], v[218:221], v[10:13]
	v_mfma_f32_16x16x32_bf16 v[62:65], v[134:137], v[192:195], v[62:65]
	v_mfma_f32_16x16x32_bf16 v[58:61], v[162:165], v[192:195], v[58:61]
	v_mfma_f32_16x16x32_bf16 v[46:49], v[134:137], v[200:203], v[46:49]
	v_mfma_f32_16x16x32_bf16 v[42:45], v[162:165], v[200:203], v[42:45]
	v_mfma_f32_16x16x32_bf16 v[30:33], v[134:137], v[214:217], v[30:33]
	v_mfma_f32_16x16x32_bf16 v[26:29], v[162:165], v[214:217], v[26:29]
	v_mfma_f32_16x16x32_bf16 v[14:17], v[134:137], v[222:225], v[14:17]
	v_mfma_f32_16x16x32_bf16 v[10:13], v[162:165], v[222:225], v[10:13]
	v_mfma_f32_16x16x32_bf16 v[54:57], v[166:169], v[188:191], v[54:57]
	v_mfma_f32_16x16x32_bf16 v[50:53], v[180:183], v[188:191], v[50:53]
	v_mfma_f32_16x16x32_bf16 v[38:41], v[166:169], v[196:199], v[38:41]
	v_mfma_f32_16x16x32_bf16 v[34:37], v[180:183], v[196:199], v[34:37]
	v_mfma_f32_16x16x32_bf16 v[22:25], v[166:169], v[210:213], v[22:25]
	v_mfma_f32_16x16x32_bf16 v[18:21], v[180:183], v[210:213], v[18:21]
	v_mfma_f32_16x16x32_bf16 v[6:9], v[166:169], v[218:221], v[6:9]
	v_mfma_f32_16x16x32_bf16 v[2:5], v[180:183], v[218:221], v[2:5]
	v_mfma_f32_16x16x32_bf16 v[54:57], v[170:173], v[192:195], v[54:57]
	v_mfma_f32_16x16x32_bf16 v[50:53], v[184:187], v[192:195], v[50:53]
	v_mfma_f32_16x16x32_bf16 v[38:41], v[170:173], v[200:203], v[38:41]
	v_mfma_f32_16x16x32_bf16 v[34:37], v[184:187], v[200:203], v[34:37]
	v_mfma_f32_16x16x32_bf16 v[22:25], v[170:173], v[214:217], v[22:25]
	v_mfma_f32_16x16x32_bf16 v[18:21], v[184:187], v[214:217], v[18:21]
	v_mfma_f32_16x16x32_bf16 v[6:9], v[170:173], v[222:225], v[6:9]
	v_mfma_f32_16x16x32_bf16 v[2:5], v[184:187], v[222:225], v[2:5]
	s_barrier
	s_add_i32 s53, s53, 2
	s_add_u32 s6, s6, 0x100
	s_addc_u32 s7, s7, 0
	s_add_u32 s41, s41, 0x100
	s_addc_u32 s52, s52, 0
	s_cmp_gt_u32 s53, 29
	s_cbranch_scc0 .LBB0_604
	s_setprio 0
	s_and_b64 vcc, exec, s[12:13]
	s_cbranch_vccz .LBB0_607
	s_barrier

.LBB0_727:
	s_add_u32 s18, s46, 0x100
	v_mov_b32_e32 v2, 0
	s_addc_u32 s19, s47, 0
	s_mov_b32 s25, -2
	v_mov_b32_e32 v3, v2
	v_mov_b32_e32 v4, v2
	v_mov_b32_e32 v5, v2
	v_mov_b32_e32 v6, v2
	v_mov_b32_e32 v7, v2
	v_mov_b32_e32 v8, v2
	v_mov_b32_e32 v9, v2
	v_mov_b32_e32 v18, v2
	v_mov_b32_e32 v19, v2
	v_mov_b32_e32 v20, v2
	v_mov_b32_e32 v21, v2
	v_mov_b32_e32 v22, v2
	v_mov_b32_e32 v23, v2
	v_mov_b32_e32 v24, v2
	v_mov_b32_e32 v25, v2
	v_mov_b32_e32 v34, v2
	v_mov_b32_e32 v35, v2
	v_mov_b32_e32 v36, v2
	v_mov_b32_e32 v37, v2
	v_mov_b32_e32 v38, v2
	v_mov_b32_e32 v39, v2
	v_mov_b32_e32 v40, v2
	v_mov_b32_e32 v41, v2
	v_mov_b32_e32 v66, v2
	v_mov_b32_e32 v67, v2
	v_mov_b32_e32 v68, v2
	v_mov_b32_e32 v69, v2
	v_mov_b32_e32 v70, v2
	v_mov_b32_e32 v71, v2
	v_mov_b32_e32 v72, v2
	v_mov_b32_e32 v73, v2
	v_mov_b32_e32 v10, v2
	s_waitcnt lgkmcnt(0)
	v_mov_b32_e32 v11, v2
	v_mov_b32_e32 v12, v2
	v_mov_b32_e32 v13, v2
	v_mov_b32_e32 v14, v2
	v_mov_b32_e32 v15, v2
	v_mov_b32_e32 v16, v2
	v_mov_b32_e32 v17, v2
	v_mov_b32_e32 v26, v2
	v_mov_b32_e32 v27, v2
	v_mov_b32_e32 v28, v2
	v_mov_b32_e32 v29, v2
	v_mov_b32_e32 v30, v2
	v_mov_b32_e32 v31, v2
	v_mov_b32_e32 v32, v2
	v_mov_b32_e32 v33, v2
	v_mov_b32_e32 v58, v2
	v_mov_b32_e32 v59, v2
	v_mov_b32_e32 v60, v2
	v_mov_b32_e32 v61, v2
	v_mov_b32_e32 v62, v2
	v_mov_b32_e32 v63, v2
	v_mov_b32_e32 v64, v2
	v_mov_b32_e32 v65, v2
	v_mov_b32_e32 v74, v2
	v_mov_b32_e32 v75, v2
	v_mov_b32_e32 v76, v2
	v_mov_b32_e32 v77, v2
	v_mov_b32_e32 v78, v2
	v_mov_b32_e32 v79, v2
	v_mov_b32_e32 v80, v2
	v_mov_b32_e32 v81, v2
	v_mov_b32_e32 v82, v2
	v_mov_b32_e32 v83, v2
	v_mov_b32_e32 v84, v2
	v_mov_b32_e32 v85, v2
	v_mov_b32_e32 v86, v2
	v_mov_b32_e32 v87, v2
	v_mov_b32_e32 v88, v2
	v_mov_b32_e32 v89, v2
	v_mov_b32_e32 v98, v2
	v_mov_b32_e32 v99, v2
	v_mov_b32_e32 v100, v2
	v_mov_b32_e32 v101, v2
	v_mov_b32_e32 v102, v2
	v_mov_b32_e32 v103, v2
	v_mov_b32_e32 v104, v2
	v_mov_b32_e32 v105, v2
	v_mov_b32_e32 v114, v2
	v_mov_b32_e32 v115, v2
	v_mov_b32_e32 v116, v2
	v_mov_b32_e32 v117, v2
	v_mov_b32_e32 v118, v2
	v_mov_b32_e32 v119, v2
	v_mov_b32_e32 v120, v2
	v_mov_b32_e32 v121, v2
	v_mov_b32_e32 v130, v2
	v_mov_b32_e32 v131, v2
	v_mov_b32_e32 v132, v2
	v_mov_b32_e32 v133, v2
	v_mov_b32_e32 v134, v2
	v_mov_b32_e32 v135, v2
	v_mov_b32_e32 v136, v2
	v_mov_b32_e32 v137, v2
	v_mov_b32_e32 v90, v2
	v_mov_b32_e32 v91, v2
	v_mov_b32_e32 v92, v2
	v_mov_b32_e32 v93, v2
	v_mov_b32_e32 v94, v2
	v_mov_b32_e32 v95, v2
	v_mov_b32_e32 v96, v2
	v_mov_b32_e32 v97, v2
	v_mov_b32_e32 v106, v2
	v_mov_b32_e32 v107, v2
	v_mov_b32_e32 v108, v2
	v_mov_b32_e32 v109, v2
	v_mov_b32_e32 v110, v2
	v_mov_b32_e32 v111, v2
	v_mov_b32_e32 v112, v2
	v_mov_b32_e32 v113, v2
	v_mov_b32_e32 v122, v2
	v_mov_b32_e32 v123, v2
	v_mov_b32_e32 v124, v2
	v_mov_b32_e32 v125, v2
	v_mov_b32_e32 v126, v2
	v_mov_b32_e32 v127, v2
	v_mov_b32_e32 v128, v2
	v_mov_b32_e32 v129, v2
	v_mov_b32_e32 v138, v2
	v_mov_b32_e32 v139, v2
	v_mov_b32_e32 v140, v2
	v_mov_b32_e32 v141, v2
	v_mov_b32_e32 v142, v2
	v_mov_b32_e32 v143, v2
	v_mov_b32_e32 v144, v2
	v_mov_b32_e32 v145, v2
	v_readfirstlane_b32 s98, v146
	s_nop 3
	s_lshr_b32 s98, s98, 6
	s_cmp_ge_u32 s98, 4
	s_cbranch_scc0 .Lgprio3
	s_setprio 1
.Lgprio3:
.LBB0_728:
	s_add_u32 s42, s22, 0x100
	s_addc_u32 s43, s23, 0
	s_add_i32 s50, 0, 0x10000
	s_cmpk_eq_i32 s25, 0x54
	s_cselect_b32 s49, s21, s43
	s_cselect_b32 s48, s20, s42
	s_cselect_b32 s47, s45, s19
	s_cselect_b32 s46, s44, s18
	s_add_i32 s51, 0, 0x14000
	v_add_u32_e32 v54, s50, v176
	v_add_u32_e32 v179, s51, v176
	ds_read_b128 v[42:45], v54
	ds_read_b128 v[46:49], v54 offset:1024
	ds_read_b128 v[50:53], v54 offset:2048
	ds_read_b128 v[54:57], v54 offset:3072
	ds_read_b128 v[154:157], v179
	ds_read_b128 v[168:171], v179 offset:1024
	ds_read_b128 v[172:175], v179 offset:2048
	ds_read_b128 v[180:183], v179 offset:3072
	s_add_i32 m0, s33, 0xc000
	ds_read_b128 v[184:187], v178
	ds_read_b128 v[188:191], v178 offset:1024
	ds_read_b128 v[192:195], v178 offset:2048
	ds_read_b128 v[196:199], v178 offset:3072
	ds_read_b128 v[200:203], v178 offset:4096
	ds_read_b128 v[210:213], v178 offset:5120
	ds_read_b128 v[214:217], v178 offset:6144
	ds_read_b128 v[218:221], v178 offset:7168
	global_load_lds_dwordx4 v164, s[22:23]
	s_add_i32 m0, s33, 0xe000
	s_nop 0
	global_load_lds_dwordx4 v166, s[22:23]
	s_waitcnt vmcnt(8)
	s_waitcnt lgkmcnt(0)
	s_barrier
	s_waitcnt lgkmcnt(0)
	v_mfma_f32_16x16x32_bf16 v[142:145], v[42:45], v[184:187], v[142:145]
	v_mfma_f32_16x16x32_bf16 v[138:141], v[50:53], v[184:187], v[138:141]
	v_mfma_f32_16x16x32_bf16 v[126:129], v[42:45], v[192:195], v[126:129]
	v_mfma_f32_16x16x32_bf16 v[122:125], v[50:53], v[192:195], v[122:125]
	v_mfma_f32_16x16x32_bf16 v[110:113], v[42:45], v[200:203], v[110:113]
	v_mfma_f32_16x16x32_bf16 v[106:109], v[50:53], v[200:203], v[106:109]
	v_mfma_f32_16x16x32_bf16 v[94:97], v[42:45], v[214:217], v[94:97]
	v_mfma_f32_16x16x32_bf16 v[90:93], v[50:53], v[214:217], v[90:93]
	v_mfma_f32_16x16x32_bf16 v[142:145], v[46:49], v[188:191], v[142:145]
	v_mfma_f32_16x16x32_bf16 v[138:141], v[54:57], v[188:191], v[138:141]
	v_mfma_f32_16x16x32_bf16 v[126:129], v[46:49], v[196:199], v[126:129]
	v_mfma_f32_16x16x32_bf16 v[122:125], v[54:57], v[196:199], v[122:125]
	v_mfma_f32_16x16x32_bf16 v[110:113], v[46:49], v[210:213], v[110:113]
	v_mfma_f32_16x16x32_bf16 v[106:109], v[54:57], v[210:213], v[106:109]
	v_mfma_f32_16x16x32_bf16 v[94:97], v[46:49], v[218:221], v[94:97]
	v_mfma_f32_16x16x32_bf16 v[90:93], v[54:57], v[218:221], v[90:93]
	v_mfma_f32_16x16x32_bf16 v[134:137], v[154:157], v[184:187], v[134:137]
	v_mfma_f32_16x16x32_bf16 v[130:133], v[172:175], v[184:187], v[130:133]
	v_mfma_f32_16x16x32_bf16 v[118:121], v[154:157], v[192:195], v[118:121]
	v_mfma_f32_16x16x32_bf16 v[114:117], v[172:175], v[192:195], v[114:117]
	v_mfma_f32_16x16x32_bf16 v[102:105], v[154:157], v[200:203], v[102:105]
	v_mfma_f32_16x16x32_bf16 v[98:101], v[172:175], v[200:203], v[98:101]
	v_mfma_f32_16x16x32_bf16 v[86:89], v[154:157], v[214:217], v[86:89]
	v_mfma_f32_16x16x32_bf16 v[82:85], v[172:175], v[214:217], v[82:85]
	v_mfma_f32_16x16x32_bf16 v[134:137], v[168:171], v[188:191], v[134:137]
	v_mfma_f32_16x16x32_bf16 v[130:133], v[180:183], v[188:191], v[130:133]
	v_mfma_f32_16x16x32_bf16 v[118:121], v[168:171], v[196:199], v[118:121]
	v_mfma_f32_16x16x32_bf16 v[114:117], v[180:183], v[196:199], v[114:117]
	v_mfma_f32_16x16x32_bf16 v[102:105], v[168:171], v[210:213], v[102:105]
	v_mfma_f32_16x16x32_bf16 v[98:101], v[180:183], v[210:213], v[98:101]
	v_mfma_f32_16x16x32_bf16 v[86:89], v[168:171], v[218:221], v[86:89]
	v_mfma_f32_16x16x32_bf16 v[82:85], v[180:183], v[218:221], v[82:85]
	s_barrier
	s_add_i32 s22, s50, s16
	v_lshl_add_u64 v[222:223], s[46:47], 0, v[0:1]
	s_mov_b32 m0, s22
	ds_read_b128 v[184:187], v178 offset:16384
	ds_read_b128 v[188:191], v178 offset:17408
	ds_read_b128 v[192:195], v178 offset:18432
	ds_read_b128 v[196:199], v178 offset:19456
	ds_read_b128 v[200:203], v178 offset:20480
	ds_read_b128 v[210:213], v178 offset:21504
	ds_read_b128 v[214:217], v178 offset:22528
	ds_read_b128 v[218:221], v178 offset:23552
	global_load_lds_dwordx4 v[222:223], off
	s_add_i32 m0, s22, 0x2000
	s_add_u32 s22, s46, 0x160000
	v_lshl_add_u64 v[224:225], s[46:47], 0, v[158:159]
	s_addc_u32 s23, s47, 0
	s_add_i32 s50, s51, s16
	global_load_lds_dwordx4 v[224:225], off
	s_mov_b32 m0, s50
	v_lshl_add_u64 v[228:229], s[48:49], 0, v[160:161]
	global_load_lds_dwordx4 v0, s[22:23]
	s_add_i32 m0, s50, 0x2000
	s_nop 0
	global_load_lds_dwordx4 v158, s[22:23]
	v_lshl_add_u64 v[226:227], s[48:49], 0, v[162:163]
	s_mov_b32 m0, s33
	s_nop 0
	global_load_lds_dwordx4 v[226:227], off
	s_mov_b32 m0, s37
	s_nop 0
	global_load_lds_dwordx4 v[228:229], off
	s_waitcnt vmcnt(8)
	s_waitcnt lgkmcnt(0)
	s_barrier
	s_waitcnt lgkmcnt(0)
	v_mfma_f32_16x16x32_bf16 v[78:81], v[42:45], v[184:187], v[78:81]
	v_mfma_f32_16x16x32_bf16 v[74:77], v[50:53], v[184:187], v[74:77]
	v_mfma_f32_16x16x32_bf16 v[62:65], v[42:45], v[192:195], v[62:65]
	v_mfma_f32_16x16x32_bf16 v[58:61], v[50:53], v[192:195], v[58:61]
	v_mfma_f32_16x16x32_bf16 v[30:33], v[42:45], v[200:203], v[30:33]
	v_mfma_f32_16x16x32_bf16 v[26:29], v[50:53], v[200:203], v[26:29]
	v_mfma_f32_16x16x32_bf16 v[14:17], v[42:45], v[214:217], v[14:17]
	v_mfma_f32_16x16x32_bf16 v[10:13], v[50:53], v[214:217], v[10:13]
	v_mfma_f32_16x16x32_bf16 v[78:81], v[46:49], v[188:191], v[78:81]
	v_mfma_f32_16x16x32_bf16 v[74:77], v[54:57], v[188:191], v[74:77]
	v_mfma_f32_16x16x32_bf16 v[62:65], v[46:49], v[196:199], v[62:65]
	v_mfma_f32_16x16x32_bf16 v[58:61], v[54:57], v[196:199], v[58:61]
	v_mfma_f32_16x16x32_bf16 v[30:33], v[46:49], v[210:213], v[30:33]
	v_mfma_f32_16x16x32_bf16 v[26:29], v[54:57], v[210:213], v[26:29]
	v_mfma_f32_16x16x32_bf16 v[14:17], v[46:49], v[218:221], v[14:17]
	v_mfma_f32_16x16x32_bf16 v[10:13], v[54:57], v[218:221], v[10:13]
	v_mfma_f32_16x16x32_bf16 v[38:41], v[154:157], v[192:195], v[38:41]
	v_mfma_f32_16x16x32_bf16 v[34:37], v[172:175], v[192:195], v[34:37]
	v_mfma_f32_16x16x32_bf16 v[22:25], v[154:157], v[200:203], v[22:25]
	v_mfma_f32_16x16x32_bf16 v[18:21], v[172:175], v[200:203], v[18:21]
	v_mfma_f32_16x16x32_bf16 v[6:9], v[154:157], v[214:217], v[6:9]
	v_mfma_f32_16x16x32_bf16 v[2:5], v[172:175], v[214:217], v[2:5]
	v_mfma_f32_16x16x32_bf16 v[42:45], v[154:157], v[184:187], v[70:73]
	v_mfma_f32_16x16x32_bf16 v[46:49], v[172:175], v[184:187], v[66:69]
	v_mfma_f32_16x16x32_bf16 v[38:41], v[168:171], v[196:199], v[38:41]
	v_mfma_f32_16x16x32_bf16 v[34:37], v[180:183], v[196:199], v[34:37]
	v_mfma_f32_16x16x32_bf16 v[22:25], v[168:171], v[210:213], v[22:25]
	v_mfma_f32_16x16x32_bf16 v[18:21], v[180:183], v[210:213], v[18:21]
	v_mfma_f32_16x16x32_bf16 v[6:9], v[168:171], v[218:221], v[6:9]
	v_mfma_f32_16x16x32_bf16 v[2:5], v[180:183], v[218:221], v[2:5]
	v_mfma_f32_16x16x32_bf16 v[42:45], v[168:171], v[188:191], v[42:45]
	v_mfma_f32_16x16x32_bf16 v[46:49], v[180:183], v[188:191], v[46:49]
	s_barrier
	s_add_i32 s50, 0, 0x18000
	s_add_i32 s51, 0, 0x1c000
	v_add_u32_e32 v70, s50, v176
	v_add_u32_e32 v179, s51, v176
	ds_read_b128 v[50:53], v70
	ds_read_b128 v[54:57], v70 offset:1024
	ds_read_b128 v[66:69], v70 offset:2048
	ds_read_b128 v[70:73], v70 offset:3072
	ds_read_b128 v[154:157], v179
	ds_read_b128 v[168:171], v179 offset:1024
	ds_read_b128 v[172:175], v179 offset:2048
	ds_read_b128 v[180:183], v179 offset:3072
	s_add_u32 s22, s48, 0x160000
	s_addc_u32 s23, s49, 0
	s_mov_b32 m0, s52
	ds_read_b128 v[184:187], v178 offset:32768
	ds_read_b128 v[188:191], v178 offset:33792
	ds_read_b128 v[192:195], v178 offset:34816
	ds_read_b128 v[196:199], v178 offset:35840
	ds_read_b128 v[200:203], v178 offset:36864
	ds_read_b128 v[210:213], v178 offset:37888
	ds_read_b128 v[214:217], v178 offset:38912
	ds_read_b128 v[218:221], v178 offset:39936
	global_load_lds_dwordx4 v162, s[22:23]
	s_mov_b32 m0, s53
	s_nop 0
	global_load_lds_dwordx4 v160, s[22:23]
	s_waitcnt vmcnt(8)
	s_waitcnt lgkmcnt(0)
	s_barrier
	s_waitcnt lgkmcnt(0)
	v_mfma_f32_16x16x32_bf16 v[142:145], v[50:53], v[184:187], v[142:145]
	v_mfma_f32_16x16x32_bf16 v[138:141], v[66:69], v[184:187], v[138:141]
	v_mfma_f32_16x16x32_bf16 v[126:129], v[50:53], v[192:195], v[126:129]
	v_mfma_f32_16x16x32_bf16 v[122:125], v[66:69], v[192:195], v[122:125]
	v_mfma_f32_16x16x32_bf16 v[110:113], v[50:53], v[200:203], v[110:113]
	v_mfma_f32_16x16x32_bf16 v[106:109], v[66:69], v[200:203], v[106:109]
	v_mfma_f32_16x16x32_bf16 v[94:97], v[50:53], v[214:217], v[94:97]
	v_mfma_f32_16x16x32_bf16 v[90:93], v[66:69], v[214:217], v[90:93]
	v_mfma_f32_16x16x32_bf16 v[142:145], v[54:57], v[188:191], v[142:145]
	v_mfma_f32_16x16x32_bf16 v[138:141], v[70:73], v[188:191], v[138:141]
	v_mfma_f32_16x16x32_bf16 v[126:129], v[54:57], v[196:199], v[126:129]
	v_mfma_f32_16x16x32_bf16 v[122:125], v[70:73], v[196:199], v[122:125]
	v_mfma_f32_16x16x32_bf16 v[110:113], v[54:57], v[210:213], v[110:113]
	v_mfma_f32_16x16x32_bf16 v[106:109], v[70:73], v[210:213], v[106:109]
	v_mfma_f32_16x16x32_bf16 v[94:97], v[54:57], v[218:221], v[94:97]
	v_mfma_f32_16x16x32_bf16 v[90:93], v[70:73], v[218:221], v[90:93]
	v_mfma_f32_16x16x32_bf16 v[134:137], v[154:157], v[184:187], v[134:137]
	v_mfma_f32_16x16x32_bf16 v[130:133], v[172:175], v[184:187], v[130:133]
	v_mfma_f32_16x16x32_bf16 v[118:121], v[154:157], v[192:195], v[118:121]
	v_mfma_f32_16x16x32_bf16 v[114:117], v[172:175], v[192:195], v[114:117]
	v_mfma_f32_16x16x32_bf16 v[102:105], v[154:157], v[200:203], v[102:105]
	v_mfma_f32_16x16x32_bf16 v[98:101], v[172:175], v[200:203], v[98:101]
	v_mfma_f32_16x16x32_bf16 v[86:89], v[154:157], v[214:217], v[86:89]
	v_mfma_f32_16x16x32_bf16 v[82:85], v[172:175], v[214:217], v[82:85]
	v_mfma_f32_16x16x32_bf16 v[134:137], v[168:171], v[188:191], v[134:137]
	v_mfma_f32_16x16x32_bf16 v[130:133], v[180:183], v[188:191], v[130:133]
	v_mfma_f32_16x16x32_bf16 v[118:121], v[168:171], v[196:199], v[118:121]
	v_mfma_f32_16x16x32_bf16 v[114:117], v[180:183], v[196:199], v[114:117]
	v_mfma_f32_16x16x32_bf16 v[102:105], v[168:171], v[210:213], v[102:105]
	v_mfma_f32_16x16x32_bf16 v[98:101], v[180:183], v[210:213], v[98:101]
	v_mfma_f32_16x16x32_bf16 v[86:89], v[168:171], v[218:221], v[86:89]
	v_mfma_f32_16x16x32_bf16 v[82:85], v[180:183], v[218:221], v[82:85]
	s_barrier
	s_add_i32 s22, s50, s16
	v_lshl_add_u64 v[222:223], v[222:223], 0, s[34:35]
	s_mov_b32 m0, s22
	ds_read_b128 v[184:187], v178 offset:49152
	ds_read_b128 v[188:191], v178 offset:50176
	ds_read_b128 v[192:195], v178 offset:51200
	ds_read_b128 v[196:199], v178 offset:52224
	ds_read_b128 v[200:203], v178 offset:53248
	ds_read_b128 v[210:213], v178 offset:54272
	ds_read_b128 v[214:217], v178 offset:55296
	ds_read_b128 v[218:221], v178 offset:56320
	global_load_lds_dwordx4 v[222:223], off
	s_add_i32 m0, s22, 0x2000
	s_add_u32 s22, s46, 0x160080
	v_lshl_add_u64 v[222:223], v[224:225], 0, s[34:35]
	s_addc_u32 s23, s47, 0
	s_add_i32 s46, s51, s16
	global_load_lds_dwordx4 v[222:223], off
	s_mov_b32 m0, s46
	s_nop 0
	global_load_lds_dwordx4 v0, s[22:23]
	s_add_i32 m0, s46, 0x2000
	s_nop 0
	global_load_lds_dwordx4 v158, s[22:23]
	v_lshl_add_u64 v[222:223], v[226:227], 0, s[34:35]
	s_mov_b32 m0, s55
	s_nop 0
	global_load_lds_dwordx4 v[222:223], off
	v_lshl_add_u64 v[222:223], v[228:229], 0, s[34:35]
	s_mov_b32 m0, s56
	s_nop 0
	global_load_lds_dwordx4 v[222:223], off
	s_waitcnt vmcnt(8)
	s_waitcnt lgkmcnt(0)
	s_barrier
	s_waitcnt lgkmcnt(0)
	v_mfma_f32_16x16x32_bf16 v[78:81], v[50:53], v[184:187], v[78:81]
	v_mfma_f32_16x16x32_bf16 v[74:77], v[66:69], v[184:187], v[74:77]
	v_mfma_f32_16x16x32_bf16 v[62:65], v[50:53], v[192:195], v[62:65]
	v_mfma_f32_16x16x32_bf16 v[58:61], v[66:69], v[192:195], v[58:61]
	v_mfma_f32_16x16x32_bf16 v[30:33], v[50:53], v[200:203], v[30:33]
	v_mfma_f32_16x16x32_bf16 v[26:29], v[66:69], v[200:203], v[26:29]
	v_mfma_f32_16x16x32_bf16 v[14:17], v[50:53], v[214:217], v[14:17]
	v_mfma_f32_16x16x32_bf16 v[10:13], v[66:69], v[214:217], v[10:13]
	v_mfma_f32_16x16x32_bf16 v[78:81], v[54:57], v[188:191], v[78:81]
	v_mfma_f32_16x16x32_bf16 v[74:77], v[70:73], v[188:191], v[74:77]
	v_mfma_f32_16x16x32_bf16 v[62:65], v[54:57], v[196:199], v[62:65]
	v_mfma_f32_16x16x32_bf16 v[58:61], v[70:73], v[196:199], v[58:61]
	v_mfma_f32_16x16x32_bf16 v[30:33], v[54:57], v[210:213], v[30:33]
	v_mfma_f32_16x16x32_bf16 v[26:29], v[70:73], v[210:213], v[26:29]
	v_mfma_f32_16x16x32_bf16 v[14:17], v[54:57], v[218:221], v[14:17]
	v_mfma_f32_16x16x32_bf16 v[10:13], v[70:73], v[218:221], v[10:13]
	v_mfma_f32_16x16x32_bf16 v[42:45], v[154:157], v[184:187], v[42:45]
	v_mfma_f32_16x16x32_bf16 v[70:73], v[168:171], v[188:191], v[42:45]
	v_mfma_f32_16x16x32_bf16 v[42:45], v[172:175], v[184:187], v[46:49]
	v_mfma_f32_16x16x32_bf16 v[38:41], v[154:157], v[192:195], v[38:41]
	v_mfma_f32_16x16x32_bf16 v[34:37], v[172:175], v[192:195], v[34:37]
	v_mfma_f32_16x16x32_bf16 v[22:25], v[154:157], v[200:203], v[22:25]
	v_mfma_f32_16x16x32_bf16 v[18:21], v[172:175], v[200:203], v[18:21]
	v_mfma_f32_16x16x32_bf16 v[6:9], v[154:157], v[214:217], v[6:9]
	v_mfma_f32_16x16x32_bf16 v[2:5], v[172:175], v[214:217], v[2:5]
	v_mfma_f32_16x16x32_bf16 v[66:69], v[180:183], v[188:191], v[42:45]
	v_mfma_f32_16x16x32_bf16 v[38:41], v[168:171], v[196:199], v[38:41]
	v_mfma_f32_16x16x32_bf16 v[34:37], v[180:183], v[196:199], v[34:37]
	v_mfma_f32_16x16x32_bf16 v[22:25], v[168:171], v[210:213], v[22:25]
	v_mfma_f32_16x16x32_bf16 v[18:21], v[180:183], v[210:213], v[18:21]
	v_mfma_f32_16x16x32_bf16 v[6:9], v[168:171], v[218:221], v[6:9]
	v_mfma_f32_16x16x32_bf16 v[2:5], v[180:183], v[218:221], v[2:5]
	s_barrier
	s_add_i32 s25, s25, 2
	s_add_u32 s18, s18, 0x100
	s_addc_u32 s19, s19, 0
	s_cmpk_gt_u32 s25, 0x55
	s_mov_b64 s[22:23], s[42:43]
	s_cbranch_scc0 .LBB0_728
	s_setprio 0
	s_and_b64 vcc, exec, s[12:13]
	s_cbranch_vccz .LBB0_731
	s_barrier
